# GEMM tiles after an epilogue: first two load segments wait with vmcnt(N + #epilogue stores) so the stores stay in flight; set-up vmcnt(0) dropped; on top of v28
# baseline (speedup 1.0000x reference)
.LBB0_187:
	s_ashr_i32 s15, s14, 31
	s_lshl_b64 s[16:17], s[14:15], 19
	s_add_u32 s16, s30, s16
	s_addc_u32 s17, s31, s17
	s_and_b64 s[18:19], s[0:1], exec
	s_cselect_b32 s3, s17, s25
	s_cselect_b32 s15, s16, s24
	s_ashr_i32 s13, s12, 31
	s_lshl_b64 s[18:19], s[12:13], 19
	s_add_u32 s18, s34, s18
	s_addc_u32 s19, s35, s19
	s_and_b64 s[26:27], s[0:1], exec
	s_cselect_b32 s13, s19, s23
	s_cselect_b32 s21, s18, s22
	s_add_u32 s48, s22, 0x100
	s_addc_u32 s49, s23, 0
	s_add_u32 s22, s24, 0x40080
	s_addc_u32 s23, s25, 0
	s_mov_b32 s50, -2
	s_cmp_lt_u32 s47, 2
	s_cbranch_scc1 .Lzfirst_1
	s_add_u32 s24, s22, 0xfffc0080
	s_addc_u32 s25, s23, -1
	s_add_i32 s51, 0, 0x10000
	s_cmp_eq_u32 s50, 12
	s_cselect_b32 s27, s3, s25
	s_cselect_b32 s26, s15, s24
	v_add_u32_e32 v142, s51, v144
	s_cselect_b32 s25, s13, s49
	s_cselect_b32 s24, s21, s48
	s_add_i32 s54, 0, 0x14000
	ds_read_b128 v[138:141], v142
	ds_read_b128 v[146:149], v142 offset:1024
	ds_read_b128 v[150:153], v142 offset:2048
	ds_read_b128 v[154:157], v142 offset:3072
	v_add_u32_e32 v142, s54, v144
	ds_read_b128 v[158:161], v142
	ds_read_b128 v[162:165], v142 offset:1024
	ds_read_b128 v[166:169], v142 offset:2048
	ds_read_b128 v[170:173], v142 offset:3072
	v_lshl_add_u64 v[142:143], s[22:23], 0, v[136:137]
	s_add_i32 m0, s37, 0xc000
	ds_read_b128 v[174:177], v145
	ds_read_b128 v[178:181], v145 offset:1024
	ds_read_b128 v[182:185], v145 offset:2048
	ds_read_b128 v[186:189], v145 offset:3072
	ds_read_b128 v[190:193], v145 offset:4096
	ds_read_b128 v[194:197], v145 offset:5120
	ds_read_b128 v[198:201], v145 offset:6144
	ds_read_b128 v[202:205], v145 offset:7168
	global_load_lds_dwordx4 v[142:143], off
	v_lshl_add_u64 v[142:143], s[22:23], 0, v[134:135]
	s_add_i32 m0, s37, 0xe000
	s_nop 0
	global_load_lds_dwordx4 v[142:143], off
	s_waitcnt vmcnt(24)
	s_waitcnt lgkmcnt(0)
	s_barrier
	s_setprio 1
	s_waitcnt lgkmcnt(0)
	v_mfma_f32_16x16x32_bf16 v[124:127], v[138:141], v[174:177], 0
	v_mfma_f32_16x16x32_bf16 v[120:123], v[150:153], v[174:177], 0
	v_mfma_f32_16x16x32_bf16 v[112:115], v[138:141], v[182:185], 0
	v_mfma_f32_16x16x32_bf16 v[104:107], v[150:153], v[182:185], 0
	v_mfma_f32_16x16x32_bf16 v[96:99], v[138:141], v[190:193], 0
	v_mfma_f32_16x16x32_bf16 v[88:91], v[150:153], v[190:193], 0
	v_mfma_f32_16x16x32_bf16 v[80:83], v[138:141], v[198:201], 0
	v_mfma_f32_16x16x32_bf16 v[72:75], v[150:153], v[198:201], 0
	v_mfma_f32_16x16x32_bf16 v[124:127], v[146:149], v[178:181], v[124:127]
	v_mfma_f32_16x16x32_bf16 v[120:123], v[154:157], v[178:181], v[120:123]
	v_mfma_f32_16x16x32_bf16 v[112:115], v[146:149], v[186:189], v[112:115]
	v_mfma_f32_16x16x32_bf16 v[104:107], v[154:157], v[186:189], v[104:107]
	v_mfma_f32_16x16x32_bf16 v[96:99], v[146:149], v[194:197], v[96:99]
	v_mfma_f32_16x16x32_bf16 v[88:91], v[154:157], v[194:197], v[88:91]
	v_mfma_f32_16x16x32_bf16 v[80:83], v[146:149], v[202:205], v[80:83]
	v_mfma_f32_16x16x32_bf16 v[72:75], v[154:157], v[202:205], v[72:75]
	s_setprio 0
	s_setprio 1
	v_mfma_f32_16x16x32_bf16 v[116:119], v[158:161], v[174:177], 0
	v_mfma_f32_16x16x32_bf16 v[108:111], v[166:169], v[174:177], 0
	v_mfma_f32_16x16x32_bf16 v[100:103], v[158:161], v[182:185], 0
	v_mfma_f32_16x16x32_bf16 v[92:95], v[166:169], v[182:185], 0
	v_mfma_f32_16x16x32_bf16 v[84:87], v[158:161], v[190:193], 0
	v_mfma_f32_16x16x32_bf16 v[76:79], v[166:169], v[190:193], 0
	v_mfma_f32_16x16x32_bf16 v[68:71], v[158:161], v[198:201], 0
	v_mfma_f32_16x16x32_bf16 v[64:67], v[166:169], v[198:201], 0
	v_mfma_f32_16x16x32_bf16 v[116:119], v[162:165], v[178:181], v[116:119]
	v_mfma_f32_16x16x32_bf16 v[108:111], v[170:173], v[178:181], v[108:111]
	v_mfma_f32_16x16x32_bf16 v[100:103], v[162:165], v[186:189], v[100:103]
	v_mfma_f32_16x16x32_bf16 v[92:95], v[170:173], v[186:189], v[92:95]
	v_mfma_f32_16x16x32_bf16 v[84:87], v[162:165], v[194:197], v[84:87]
	v_mfma_f32_16x16x32_bf16 v[76:79], v[170:173], v[194:197], v[76:79]
	v_mfma_f32_16x16x32_bf16 v[68:71], v[162:165], v[202:205], v[68:71]
	v_mfma_f32_16x16x32_bf16 v[64:67], v[170:173], v[202:205], v[64:67]
	s_setprio 0
	s_barrier
	s_add_i32 s51, s51, s36
	v_lshl_add_u64 v[142:143], s[24:25], 0, v[232:233]
	s_mov_b32 m0, s51
	ds_read_b128 v[174:177], v145 offset:16384
	ds_read_b128 v[178:181], v145 offset:17408
	ds_read_b128 v[182:185], v145 offset:18432
	ds_read_b128 v[186:189], v145 offset:19456
	ds_read_b128 v[190:193], v145 offset:20480
	ds_read_b128 v[194:197], v145 offset:21504
	ds_read_b128 v[198:201], v145 offset:22528
	ds_read_b128 v[202:205], v145 offset:23552
	global_load_lds_dwordx4 v[142:143], off
	s_add_i32 m0, s51, 0x2000
	s_add_u32 s52, s24, 0x40000
	v_lshl_add_u64 v[206:207], s[24:25], 0, v[132:133]
	s_addc_u32 s53, s25, 0
	s_add_i32 s51, s54, s36
	global_load_lds_dwordx4 v[206:207], off
	v_lshl_add_u64 v[208:209], s[52:53], 0, v[232:233]
	s_mov_b32 m0, s51
	v_lshl_add_u64 v[210:211], s[26:27], 0, v[130:131]
	global_load_lds_dwordx4 v[208:209], off
	v_lshl_add_u64 v[208:209], s[52:53], 0, v[132:133]
	s_add_i32 m0, s51, 0x2000
	s_nop 0
	global_load_lds_dwordx4 v[208:209], off
	v_lshl_add_u64 v[208:209], s[26:27], 0, v[128:129]
	s_waitcnt vmcnt(22)
	s_waitcnt lgkmcnt(0)
	s_barrier
	s_setprio 1
	s_waitcnt lgkmcnt(0)
	v_mfma_f32_16x16x32_bf16 v[60:63], v[138:141], v[174:177], 0
	v_mfma_f32_16x16x32_bf16 v[56:59], v[150:153], v[174:177], 0
	v_mfma_f32_16x16x32_bf16 v[48:51], v[138:141], v[182:185], 0
	v_mfma_f32_16x16x32_bf16 v[40:43], v[150:153], v[182:185], 0
	v_mfma_f32_16x16x32_bf16 v[32:35], v[138:141], v[190:193], 0
	v_mfma_f32_16x16x32_bf16 v[24:27], v[150:153], v[190:193], 0
	v_mfma_f32_16x16x32_bf16 v[16:19], v[138:141], v[198:201], 0
	v_mfma_f32_16x16x32_bf16 v[8:11], v[150:153], v[198:201], 0
	v_mfma_f32_16x16x32_bf16 v[60:63], v[146:149], v[178:181], v[60:63]
	v_mfma_f32_16x16x32_bf16 v[56:59], v[154:157], v[178:181], v[56:59]
	v_mfma_f32_16x16x32_bf16 v[48:51], v[146:149], v[186:189], v[48:51]
	v_mfma_f32_16x16x32_bf16 v[40:43], v[154:157], v[186:189], v[40:43]
	v_mfma_f32_16x16x32_bf16 v[32:35], v[146:149], v[194:197], v[32:35]
	v_mfma_f32_16x16x32_bf16 v[24:27], v[154:157], v[194:197], v[24:27]
	v_mfma_f32_16x16x32_bf16 v[16:19], v[146:149], v[202:205], v[16:19]
	v_mfma_f32_16x16x32_bf16 v[8:11], v[154:157], v[202:205], v[8:11]
	s_setprio 0
	s_setprio 1
	v_mfma_f32_16x16x32_bf16 v[52:55], v[158:161], v[174:177], 0
	v_mfma_f32_16x16x32_bf16 v[44:47], v[166:169], v[174:177], 0
	v_mfma_f32_16x16x32_bf16 v[36:39], v[158:161], v[182:185], 0
	v_mfma_f32_16x16x32_bf16 v[28:31], v[166:169], v[182:185], 0
	v_mfma_f32_16x16x32_bf16 v[20:23], v[158:161], v[190:193], 0
	v_mfma_f32_16x16x32_bf16 v[12:15], v[166:169], v[190:193], 0
	v_mfma_f32_16x16x32_bf16 v[4:7], v[158:161], v[198:201], 0
	v_mfma_f32_16x16x32_bf16 v[0:3], v[166:169], v[198:201], 0
	v_mfma_f32_16x16x32_bf16 v[52:55], v[162:165], v[178:181], v[52:55]
	v_mfma_f32_16x16x32_bf16 v[44:47], v[170:173], v[178:181], v[44:47]
	v_mfma_f32_16x16x32_bf16 v[36:39], v[162:165], v[186:189], v[36:39]
	v_mfma_f32_16x16x32_bf16 v[28:31], v[170:173], v[186:189], v[28:31]
	v_mfma_f32_16x16x32_bf16 v[20:23], v[162:165], v[194:197], v[20:23]
	v_mfma_f32_16x16x32_bf16 v[12:15], v[170:173], v[194:197], v[12:15]
	v_mfma_f32_16x16x32_bf16 v[4:7], v[162:165], v[202:205], v[4:7]
	v_mfma_f32_16x16x32_bf16 v[0:3], v[170:173], v[202:205], v[0:3]
	s_setprio 0
	s_barrier
	s_branch .Lzmid_1
.Lzfirst_1:
	s_add_u32 s24, s22, 0xfffc0080
	s_addc_u32 s25, s23, -1
	s_add_i32 s51, 0, 0x10000
	s_cmp_eq_u32 s50, 12
	s_cselect_b32 s27, s3, s25
	s_cselect_b32 s26, s15, s24
	v_add_u32_e32 v142, s51, v144
	s_cselect_b32 s25, s13, s49
	s_cselect_b32 s24, s21, s48
	s_add_i32 s54, 0, 0x14000
	ds_read_b128 v[138:141], v142
	ds_read_b128 v[146:149], v142 offset:1024
	ds_read_b128 v[150:153], v142 offset:2048
	ds_read_b128 v[154:157], v142 offset:3072
	v_add_u32_e32 v142, s54, v144
	ds_read_b128 v[158:161], v142
	ds_read_b128 v[162:165], v142 offset:1024
	ds_read_b128 v[166:169], v142 offset:2048
	ds_read_b128 v[170:173], v142 offset:3072
	v_lshl_add_u64 v[142:143], s[22:23], 0, v[136:137]
	s_add_i32 m0, s37, 0xc000
	ds_read_b128 v[174:177], v145
	ds_read_b128 v[178:181], v145 offset:1024
	ds_read_b128 v[182:185], v145 offset:2048
	ds_read_b128 v[186:189], v145 offset:3072
	ds_read_b128 v[190:193], v145 offset:4096
	ds_read_b128 v[194:197], v145 offset:5120
	ds_read_b128 v[198:201], v145 offset:6144
	ds_read_b128 v[202:205], v145 offset:7168
	global_load_lds_dwordx4 v[142:143], off
	v_lshl_add_u64 v[142:143], s[22:23], 0, v[134:135]
	s_add_i32 m0, s37, 0xe000
	s_nop 0
	global_load_lds_dwordx4 v[142:143], off
	s_waitcnt vmcnt(8)
	s_waitcnt lgkmcnt(0)
	s_barrier
	s_setprio 1
	s_waitcnt lgkmcnt(0)
	v_mfma_f32_16x16x32_bf16 v[124:127], v[138:141], v[174:177], 0
	v_mfma_f32_16x16x32_bf16 v[120:123], v[150:153], v[174:177], 0
	v_mfma_f32_16x16x32_bf16 v[112:115], v[138:141], v[182:185], 0
	v_mfma_f32_16x16x32_bf16 v[104:107], v[150:153], v[182:185], 0
	v_mfma_f32_16x16x32_bf16 v[96:99], v[138:141], v[190:193], 0
	v_mfma_f32_16x16x32_bf16 v[88:91], v[150:153], v[190:193], 0
	v_mfma_f32_16x16x32_bf16 v[80:83], v[138:141], v[198:201], 0
	v_mfma_f32_16x16x32_bf16 v[72:75], v[150:153], v[198:201], 0
	v_mfma_f32_16x16x32_bf16 v[124:127], v[146:149], v[178:181], v[124:127]
	v_mfma_f32_16x16x32_bf16 v[120:123], v[154:157], v[178:181], v[120:123]
	v_mfma_f32_16x16x32_bf16 v[112:115], v[146:149], v[186:189], v[112:115]
	v_mfma_f32_16x16x32_bf16 v[104:107], v[154:157], v[186:189], v[104:107]
	v_mfma_f32_16x16x32_bf16 v[96:99], v[146:149], v[194:197], v[96:99]
	v_mfma_f32_16x16x32_bf16 v[88:91], v[154:157], v[194:197], v[88:91]
	v_mfma_f32_16x16x32_bf16 v[80:83], v[146:149], v[202:205], v[80:83]
	v_mfma_f32_16x16x32_bf16 v[72:75], v[154:157], v[202:205], v[72:75]
	s_setprio 0
	s_setprio 1
	v_mfma_f32_16x16x32_bf16 v[116:119], v[158:161], v[174:177], 0
	v_mfma_f32_16x16x32_bf16 v[108:111], v[166:169], v[174:177], 0
	v_mfma_f32_16x16x32_bf16 v[100:103], v[158:161], v[182:185], 0
	v_mfma_f32_16x16x32_bf16 v[92:95], v[166:169], v[182:185], 0
	v_mfma_f32_16x16x32_bf16 v[84:87], v[158:161], v[190:193], 0
	v_mfma_f32_16x16x32_bf16 v[76:79], v[166:169], v[190:193], 0
	v_mfma_f32_16x16x32_bf16 v[68:71], v[158:161], v[198:201], 0
	v_mfma_f32_16x16x32_bf16 v[64:67], v[166:169], v[198:201], 0
	v_mfma_f32_16x16x32_bf16 v[116:119], v[162:165], v[178:181], v[116:119]
	v_mfma_f32_16x16x32_bf16 v[108:111], v[170:173], v[178:181], v[108:111]
	v_mfma_f32_16x16x32_bf16 v[100:103], v[162:165], v[186:189], v[100:103]
	v_mfma_f32_16x16x32_bf16 v[92:95], v[170:173], v[186:189], v[92:95]
	v_mfma_f32_16x16x32_bf16 v[84:87], v[162:165], v[194:197], v[84:87]
	v_mfma_f32_16x16x32_bf16 v[76:79], v[170:173], v[194:197], v[76:79]
	v_mfma_f32_16x16x32_bf16 v[68:71], v[162:165], v[202:205], v[68:71]
	v_mfma_f32_16x16x32_bf16 v[64:67], v[170:173], v[202:205], v[64:67]
	s_setprio 0
	s_barrier
	s_add_i32 s51, s51, s36
	v_lshl_add_u64 v[142:143], s[24:25], 0, v[232:233]
	s_mov_b32 m0, s51
	ds_read_b128 v[174:177], v145 offset:16384
	ds_read_b128 v[178:181], v145 offset:17408
	ds_read_b128 v[182:185], v145 offset:18432
	ds_read_b128 v[186:189], v145 offset:19456
	ds_read_b128 v[190:193], v145 offset:20480
	ds_read_b128 v[194:197], v145 offset:21504
	ds_read_b128 v[198:201], v145 offset:22528
	ds_read_b128 v[202:205], v145 offset:23552
	global_load_lds_dwordx4 v[142:143], off
	s_add_i32 m0, s51, 0x2000
	s_add_u32 s52, s24, 0x40000
	v_lshl_add_u64 v[206:207], s[24:25], 0, v[132:133]
	s_addc_u32 s53, s25, 0
	s_add_i32 s51, s54, s36
	global_load_lds_dwordx4 v[206:207], off
	v_lshl_add_u64 v[208:209], s[52:53], 0, v[232:233]
	s_mov_b32 m0, s51
	v_lshl_add_u64 v[210:211], s[26:27], 0, v[130:131]
	global_load_lds_dwordx4 v[208:209], off
	v_lshl_add_u64 v[208:209], s[52:53], 0, v[132:133]
	s_add_i32 m0, s51, 0x2000
	s_nop 0
	global_load_lds_dwordx4 v[208:209], off
	v_lshl_add_u64 v[208:209], s[26:27], 0, v[128:129]
	s_waitcnt vmcnt(6)
	s_waitcnt lgkmcnt(0)
	s_barrier
	s_setprio 1
	s_waitcnt lgkmcnt(0)
	v_mfma_f32_16x16x32_bf16 v[60:63], v[138:141], v[174:177], 0
	v_mfma_f32_16x16x32_bf16 v[56:59], v[150:153], v[174:177], 0
	v_mfma_f32_16x16x32_bf16 v[48:51], v[138:141], v[182:185], 0
	v_mfma_f32_16x16x32_bf16 v[40:43], v[150:153], v[182:185], 0
	v_mfma_f32_16x16x32_bf16 v[32:35], v[138:141], v[190:193], 0
	v_mfma_f32_16x16x32_bf16 v[24:27], v[150:153], v[190:193], 0
	v_mfma_f32_16x16x32_bf16 v[16:19], v[138:141], v[198:201], 0
	v_mfma_f32_16x16x32_bf16 v[8:11], v[150:153], v[198:201], 0
	v_mfma_f32_16x16x32_bf16 v[60:63], v[146:149], v[178:181], v[60:63]
	v_mfma_f32_16x16x32_bf16 v[56:59], v[154:157], v[178:181], v[56:59]
	v_mfma_f32_16x16x32_bf16 v[48:51], v[146:149], v[186:189], v[48:51]
	v_mfma_f32_16x16x32_bf16 v[40:43], v[154:157], v[186:189], v[40:43]
	v_mfma_f32_16x16x32_bf16 v[32:35], v[146:149], v[194:197], v[32:35]
	v_mfma_f32_16x16x32_bf16 v[24:27], v[154:157], v[194:197], v[24:27]
	v_mfma_f32_16x16x32_bf16 v[16:19], v[146:149], v[202:205], v[16:19]
	v_mfma_f32_16x16x32_bf16 v[8:11], v[154:157], v[202:205], v[8:11]
	s_setprio 0
	s_setprio 1
	v_mfma_f32_16x16x32_bf16 v[52:55], v[158:161], v[174:177], 0
	v_mfma_f32_16x16x32_bf16 v[44:47], v[166:169], v[174:177], 0
	v_mfma_f32_16x16x32_bf16 v[36:39], v[158:161], v[182:185], 0
	v_mfma_f32_16x16x32_bf16 v[28:31], v[166:169], v[182:185], 0
	v_mfma_f32_16x16x32_bf16 v[20:23], v[158:161], v[190:193], 0
	v_mfma_f32_16x16x32_bf16 v[12:15], v[166:169], v[190:193], 0
	v_mfma_f32_16x16x32_bf16 v[4:7], v[158:161], v[198:201], 0
	v_mfma_f32_16x16x32_bf16 v[0:3], v[166:169], v[198:201], 0
	v_mfma_f32_16x16x32_bf16 v[52:55], v[162:165], v[178:181], v[52:55]
	v_mfma_f32_16x16x32_bf16 v[44:47], v[170:173], v[178:181], v[44:47]
	v_mfma_f32_16x16x32_bf16 v[36:39], v[162:165], v[186:189], v[36:39]
	v_mfma_f32_16x16x32_bf16 v[28:31], v[170:173], v[186:189], v[28:31]
	v_mfma_f32_16x16x32_bf16 v[20:23], v[162:165], v[194:197], v[20:23]
	v_mfma_f32_16x16x32_bf16 v[12:15], v[170:173], v[194:197], v[12:15]
	v_mfma_f32_16x16x32_bf16 v[4:7], v[162:165], v[202:205], v[4:7]
	v_mfma_f32_16x16x32_bf16 v[0:3], v[170:173], v[202:205], v[0:3]
	s_setprio 0
	s_barrier
	s_branch .Lzmid_1

.LBB0_911:
	s_ashr_i32 s15, s14, 31
	s_lshl_b64 s[16:17], s[14:15], 19
	s_add_u32 s16, s30, s16
	s_addc_u32 s17, s31, s17
	s_and_b64 s[18:19], s[2:3], exec
	s_cselect_b32 s5, s17, s25
	s_cselect_b32 s15, s16, s24
	s_ashr_i32 s13, s12, 31
	s_lshl_b64 s[18:19], s[12:13], 19
	s_add_u32 s18, s34, s18
	s_addc_u32 s19, s35, s19
	s_and_b64 s[26:27], s[2:3], exec
	s_cselect_b32 s13, s19, s23
	s_cselect_b32 s21, s18, s22
	s_add_u32 s48, s22, 0x100
	s_addc_u32 s49, s23, 0
	s_add_u32 s22, s24, 0x40080
	s_addc_u32 s23, s25, 0
	s_mov_b32 s50, -2
	s_cmp_lt_u32 s47, 2
	s_cbranch_scc1 .Lzfirst_2
	s_add_u32 s24, s22, 0xfffc0080
	s_addc_u32 s25, s23, -1
	s_add_i32 s51, 0, 0x10000
	s_cmp_eq_u32 s50, 12
	s_cselect_b32 s27, s5, s25
	s_cselect_b32 s26, s15, s24
	v_add_u32_e32 v142, s51, v144
	s_cselect_b32 s25, s13, s49
	s_cselect_b32 s24, s21, s48
	s_add_i32 s54, 0, 0x14000
	ds_read_b128 v[138:141], v142
	ds_read_b128 v[146:149], v142 offset:1024
	ds_read_b128 v[150:153], v142 offset:2048
	ds_read_b128 v[154:157], v142 offset:3072
	v_add_u32_e32 v142, s54, v144
	ds_read_b128 v[158:161], v142
	ds_read_b128 v[162:165], v142 offset:1024
	ds_read_b128 v[166:169], v142 offset:2048
	ds_read_b128 v[170:173], v142 offset:3072
	v_lshl_add_u64 v[142:143], s[22:23], 0, v[136:137]
	s_add_i32 m0, s37, 0xc000
	ds_read_b128 v[174:177], v145
	ds_read_b128 v[178:181], v145 offset:1024
	ds_read_b128 v[182:185], v145 offset:2048
	ds_read_b128 v[186:189], v145 offset:3072
	ds_read_b128 v[190:193], v145 offset:4096
	ds_read_b128 v[194:197], v145 offset:5120
	ds_read_b128 v[198:201], v145 offset:6144
	ds_read_b128 v[202:205], v145 offset:7168
	global_load_lds_dwordx4 v[142:143], off
	v_lshl_add_u64 v[142:143], s[22:23], 0, v[134:135]
	s_add_i32 m0, s37, 0xe000
	s_nop 0
	global_load_lds_dwordx4 v[142:143], off
	s_waitcnt vmcnt(24)
	s_waitcnt lgkmcnt(0)
	s_barrier
	s_setprio 1
	s_waitcnt lgkmcnt(0)
	v_mfma_f32_16x16x32_bf16 v[124:127], v[138:141], v[174:177], 0
	v_mfma_f32_16x16x32_bf16 v[120:123], v[150:153], v[174:177], 0
	v_mfma_f32_16x16x32_bf16 v[108:111], v[138:141], v[182:185], 0
	v_mfma_f32_16x16x32_bf16 v[104:107], v[150:153], v[182:185], 0
	v_mfma_f32_16x16x32_bf16 v[92:95], v[138:141], v[190:193], 0
	v_mfma_f32_16x16x32_bf16 v[88:91], v[150:153], v[190:193], 0
	v_mfma_f32_16x16x32_bf16 v[76:79], v[138:141], v[198:201], 0
	v_mfma_f32_16x16x32_bf16 v[72:75], v[150:153], v[198:201], 0
	v_mfma_f32_16x16x32_bf16 v[124:127], v[146:149], v[178:181], v[124:127]
	v_mfma_f32_16x16x32_bf16 v[120:123], v[154:157], v[178:181], v[120:123]
	v_mfma_f32_16x16x32_bf16 v[108:111], v[146:149], v[186:189], v[108:111]
	v_mfma_f32_16x16x32_bf16 v[104:107], v[154:157], v[186:189], v[104:107]
	v_mfma_f32_16x16x32_bf16 v[92:95], v[146:149], v[194:197], v[92:95]
	v_mfma_f32_16x16x32_bf16 v[88:91], v[154:157], v[194:197], v[88:91]
	v_mfma_f32_16x16x32_bf16 v[76:79], v[146:149], v[202:205], v[76:79]
	v_mfma_f32_16x16x32_bf16 v[72:75], v[154:157], v[202:205], v[72:75]
	s_setprio 0
	s_setprio 1
	v_mfma_f32_16x16x32_bf16 v[116:119], v[158:161], v[174:177], 0
	v_mfma_f32_16x16x32_bf16 v[112:115], v[166:169], v[174:177], 0
	v_mfma_f32_16x16x32_bf16 v[100:103], v[158:161], v[182:185], 0
	v_mfma_f32_16x16x32_bf16 v[96:99], v[166:169], v[182:185], 0
	v_mfma_f32_16x16x32_bf16 v[84:87], v[158:161], v[190:193], 0
	v_mfma_f32_16x16x32_bf16 v[80:83], v[166:169], v[190:193], 0
	v_mfma_f32_16x16x32_bf16 v[68:71], v[158:161], v[198:201], 0
	v_mfma_f32_16x16x32_bf16 v[64:67], v[166:169], v[198:201], 0
	v_mfma_f32_16x16x32_bf16 v[116:119], v[162:165], v[178:181], v[116:119]
	v_mfma_f32_16x16x32_bf16 v[112:115], v[170:173], v[178:181], v[112:115]
	v_mfma_f32_16x16x32_bf16 v[100:103], v[162:165], v[186:189], v[100:103]
	v_mfma_f32_16x16x32_bf16 v[96:99], v[170:173], v[186:189], v[96:99]
	v_mfma_f32_16x16x32_bf16 v[84:87], v[162:165], v[194:197], v[84:87]
	v_mfma_f32_16x16x32_bf16 v[80:83], v[170:173], v[194:197], v[80:83]
	v_mfma_f32_16x16x32_bf16 v[68:71], v[162:165], v[202:205], v[68:71]
	v_mfma_f32_16x16x32_bf16 v[64:67], v[170:173], v[202:205], v[64:67]
	s_setprio 0
	s_barrier
	s_add_i32 s51, s51, s36
	v_lshl_add_u64 v[142:143], s[24:25], 0, v[232:233]
	s_mov_b32 m0, s51
	ds_read_b128 v[174:177], v145 offset:16384
	ds_read_b128 v[178:181], v145 offset:17408
	ds_read_b128 v[182:185], v145 offset:18432
	ds_read_b128 v[186:189], v145 offset:19456
	ds_read_b128 v[190:193], v145 offset:20480
	ds_read_b128 v[194:197], v145 offset:21504
	ds_read_b128 v[198:201], v145 offset:22528
	ds_read_b128 v[202:205], v145 offset:23552
	global_load_lds_dwordx4 v[142:143], off
	s_add_i32 m0, s51, 0x2000
	s_add_u32 s52, s24, 0x40000
	v_lshl_add_u64 v[206:207], s[24:25], 0, v[132:133]
	s_addc_u32 s53, s25, 0
	s_add_i32 s51, s54, s36
	global_load_lds_dwordx4 v[206:207], off
	v_lshl_add_u64 v[208:209], s[52:53], 0, v[232:233]
	s_mov_b32 m0, s51
	v_lshl_add_u64 v[210:211], s[26:27], 0, v[130:131]
	global_load_lds_dwordx4 v[208:209], off
	v_lshl_add_u64 v[208:209], s[52:53], 0, v[132:133]
	s_add_i32 m0, s51, 0x2000
	s_nop 0
	global_load_lds_dwordx4 v[208:209], off
	v_lshl_add_u64 v[208:209], s[26:27], 0, v[128:129]
	s_waitcnt vmcnt(22)
	s_waitcnt lgkmcnt(0)
	s_barrier
	s_setprio 1
	s_waitcnt lgkmcnt(0)
	v_mfma_f32_16x16x32_bf16 v[60:63], v[138:141], v[174:177], 0
	v_mfma_f32_16x16x32_bf16 v[56:59], v[150:153], v[174:177], 0
	v_mfma_f32_16x16x32_bf16 v[44:47], v[138:141], v[182:185], 0
	v_mfma_f32_16x16x32_bf16 v[40:43], v[150:153], v[182:185], 0
	v_mfma_f32_16x16x32_bf16 v[28:31], v[138:141], v[190:193], 0
	v_mfma_f32_16x16x32_bf16 v[24:27], v[150:153], v[190:193], 0
	v_mfma_f32_16x16x32_bf16 v[12:15], v[138:141], v[198:201], 0
	v_mfma_f32_16x16x32_bf16 v[8:11], v[150:153], v[198:201], 0
	v_mfma_f32_16x16x32_bf16 v[60:63], v[146:149], v[178:181], v[60:63]
	v_mfma_f32_16x16x32_bf16 v[56:59], v[154:157], v[178:181], v[56:59]
	v_mfma_f32_16x16x32_bf16 v[44:47], v[146:149], v[186:189], v[44:47]
	v_mfma_f32_16x16x32_bf16 v[40:43], v[154:157], v[186:189], v[40:43]
	v_mfma_f32_16x16x32_bf16 v[28:31], v[146:149], v[194:197], v[28:31]
	v_mfma_f32_16x16x32_bf16 v[24:27], v[154:157], v[194:197], v[24:27]
	v_mfma_f32_16x16x32_bf16 v[12:15], v[146:149], v[202:205], v[12:15]
	v_mfma_f32_16x16x32_bf16 v[8:11], v[154:157], v[202:205], v[8:11]
	s_setprio 0
	s_setprio 1
	v_mfma_f32_16x16x32_bf16 v[52:55], v[158:161], v[174:177], 0
	v_mfma_f32_16x16x32_bf16 v[48:51], v[166:169], v[174:177], 0
	v_mfma_f32_16x16x32_bf16 v[36:39], v[158:161], v[182:185], 0
	v_mfma_f32_16x16x32_bf16 v[32:35], v[166:169], v[182:185], 0
	v_mfma_f32_16x16x32_bf16 v[20:23], v[158:161], v[190:193], 0
	v_mfma_f32_16x16x32_bf16 v[16:19], v[166:169], v[190:193], 0
	v_mfma_f32_16x16x32_bf16 v[4:7], v[158:161], v[198:201], 0
	v_mfma_f32_16x16x32_bf16 v[0:3], v[166:169], v[198:201], 0
	v_mfma_f32_16x16x32_bf16 v[52:55], v[162:165], v[178:181], v[52:55]
	v_mfma_f32_16x16x32_bf16 v[48:51], v[170:173], v[178:181], v[48:51]
	v_mfma_f32_16x16x32_bf16 v[36:39], v[162:165], v[186:189], v[36:39]
	v_mfma_f32_16x16x32_bf16 v[32:35], v[170:173], v[186:189], v[32:35]
	v_mfma_f32_16x16x32_bf16 v[20:23], v[162:165], v[194:197], v[20:23]
	v_mfma_f32_16x16x32_bf16 v[16:19], v[170:173], v[194:197], v[16:19]
	v_mfma_f32_16x16x32_bf16 v[4:7], v[162:165], v[202:205], v[4:7]
	v_mfma_f32_16x16x32_bf16 v[0:3], v[170:173], v[202:205], v[0:3]
	s_setprio 0
	s_barrier
	s_branch .Lzmid_2
.Lzfirst_2:
	s_add_u32 s24, s22, 0xfffc0080
	s_addc_u32 s25, s23, -1
	s_add_i32 s51, 0, 0x10000
	s_cmp_eq_u32 s50, 12
	s_cselect_b32 s27, s5, s25
	s_cselect_b32 s26, s15, s24
	v_add_u32_e32 v142, s51, v144
	s_cselect_b32 s25, s13, s49
	s_cselect_b32 s24, s21, s48
	s_add_i32 s54, 0, 0x14000
	ds_read_b128 v[138:141], v142
	ds_read_b128 v[146:149], v142 offset:1024
	ds_read_b128 v[150:153], v142 offset:2048
	ds_read_b128 v[154:157], v142 offset:3072
	v_add_u32_e32 v142, s54, v144
	ds_read_b128 v[158:161], v142
	ds_read_b128 v[162:165], v142 offset:1024
	ds_read_b128 v[166:169], v142 offset:2048
	ds_read_b128 v[170:173], v142 offset:3072
	v_lshl_add_u64 v[142:143], s[22:23], 0, v[136:137]
	s_add_i32 m0, s37, 0xc000
	ds_read_b128 v[174:177], v145
	ds_read_b128 v[178:181], v145 offset:1024
	ds_read_b128 v[182:185], v145 offset:2048
	ds_read_b128 v[186:189], v145 offset:3072
	ds_read_b128 v[190:193], v145 offset:4096
	ds_read_b128 v[194:197], v145 offset:5120
	ds_read_b128 v[198:201], v145 offset:6144
	ds_read_b128 v[202:205], v145 offset:7168
	global_load_lds_dwordx4 v[142:143], off
	v_lshl_add_u64 v[142:143], s[22:23], 0, v[134:135]
	s_add_i32 m0, s37, 0xe000
	s_nop 0
	global_load_lds_dwordx4 v[142:143], off
	s_waitcnt vmcnt(8)
	s_waitcnt lgkmcnt(0)
	s_barrier
	s_setprio 1
	s_waitcnt lgkmcnt(0)
	v_mfma_f32_16x16x32_bf16 v[124:127], v[138:141], v[174:177], 0
	v_mfma_f32_16x16x32_bf16 v[120:123], v[150:153], v[174:177], 0
	v_mfma_f32_16x16x32_bf16 v[108:111], v[138:141], v[182:185], 0
	v_mfma_f32_16x16x32_bf16 v[104:107], v[150:153], v[182:185], 0
	v_mfma_f32_16x16x32_bf16 v[92:95], v[138:141], v[190:193], 0
	v_mfma_f32_16x16x32_bf16 v[88:91], v[150:153], v[190:193], 0
	v_mfma_f32_16x16x32_bf16 v[76:79], v[138:141], v[198:201], 0
	v_mfma_f32_16x16x32_bf16 v[72:75], v[150:153], v[198:201], 0
	v_mfma_f32_16x16x32_bf16 v[124:127], v[146:149], v[178:181], v[124:127]
	v_mfma_f32_16x16x32_bf16 v[120:123], v[154:157], v[178:181], v[120:123]
	v_mfma_f32_16x16x32_bf16 v[108:111], v[146:149], v[186:189], v[108:111]
	v_mfma_f32_16x16x32_bf16 v[104:107], v[154:157], v[186:189], v[104:107]
	v_mfma_f32_16x16x32_bf16 v[92:95], v[146:149], v[194:197], v[92:95]
	v_mfma_f32_16x16x32_bf16 v[88:91], v[154:157], v[194:197], v[88:91]
	v_mfma_f32_16x16x32_bf16 v[76:79], v[146:149], v[202:205], v[76:79]
	v_mfma_f32_16x16x32_bf16 v[72:75], v[154:157], v[202:205], v[72:75]
	s_setprio 0
	s_setprio 1
	v_mfma_f32_16x16x32_bf16 v[116:119], v[158:161], v[174:177], 0
	v_mfma_f32_16x16x32_bf16 v[112:115], v[166:169], v[174:177], 0
	v_mfma_f32_16x16x32_bf16 v[100:103], v[158:161], v[182:185], 0
	v_mfma_f32_16x16x32_bf16 v[96:99], v[166:169], v[182:185], 0
	v_mfma_f32_16x16x32_bf16 v[84:87], v[158:161], v[190:193], 0
	v_mfma_f32_16x16x32_bf16 v[80:83], v[166:169], v[190:193], 0
	v_mfma_f32_16x16x32_bf16 v[68:71], v[158:161], v[198:201], 0
	v_mfma_f32_16x16x32_bf16 v[64:67], v[166:169], v[198:201], 0
	v_mfma_f32_16x16x32_bf16 v[116:119], v[162:165], v[178:181], v[116:119]
	v_mfma_f32_16x16x32_bf16 v[112:115], v[170:173], v[178:181], v[112:115]
	v_mfma_f32_16x16x32_bf16 v[100:103], v[162:165], v[186:189], v[100:103]
	v_mfma_f32_16x16x32_bf16 v[96:99], v[170:173], v[186:189], v[96:99]
	v_mfma_f32_16x16x32_bf16 v[84:87], v[162:165], v[194:197], v[84:87]
	v_mfma_f32_16x16x32_bf16 v[80:83], v[170:173], v[194:197], v[80:83]
	v_mfma_f32_16x16x32_bf16 v[68:71], v[162:165], v[202:205], v[68:71]
	v_mfma_f32_16x16x32_bf16 v[64:67], v[170:173], v[202:205], v[64:67]
	s_setprio 0
	s_barrier
	s_add_i32 s51, s51, s36
	v_lshl_add_u64 v[142:143], s[24:25], 0, v[232:233]
	s_mov_b32 m0, s51
	ds_read_b128 v[174:177], v145 offset:16384
	ds_read_b128 v[178:181], v145 offset:17408
	ds_read_b128 v[182:185], v145 offset:18432
	ds_read_b128 v[186:189], v145 offset:19456
	ds_read_b128 v[190:193], v145 offset:20480
	ds_read_b128 v[194:197], v145 offset:21504
	ds_read_b128 v[198:201], v145 offset:22528
	ds_read_b128 v[202:205], v145 offset:23552
	global_load_lds_dwordx4 v[142:143], off
	s_add_i32 m0, s51, 0x2000
	s_add_u32 s52, s24, 0x40000
	v_lshl_add_u64 v[206:207], s[24:25], 0, v[132:133]
	s_addc_u32 s53, s25, 0
	s_add_i32 s51, s54, s36
	global_load_lds_dwordx4 v[206:207], off
	v_lshl_add_u64 v[208:209], s[52:53], 0, v[232:233]
	s_mov_b32 m0, s51
	v_lshl_add_u64 v[210:211], s[26:27], 0, v[130:131]
	global_load_lds_dwordx4 v[208:209], off
	v_lshl_add_u64 v[208:209], s[52:53], 0, v[132:133]
	s_add_i32 m0, s51, 0x2000
	s_nop 0
	global_load_lds_dwordx4 v[208:209], off
	v_lshl_add_u64 v[208:209], s[26:27], 0, v[128:129]
	s_waitcnt vmcnt(6)
	s_waitcnt lgkmcnt(0)
	s_barrier
	s_setprio 1
	s_waitcnt lgkmcnt(0)
	v_mfma_f32_16x16x32_bf16 v[60:63], v[138:141], v[174:177], 0
	v_mfma_f32_16x16x32_bf16 v[56:59], v[150:153], v[174:177], 0
	v_mfma_f32_16x16x32_bf16 v[44:47], v[138:141], v[182:185], 0
	v_mfma_f32_16x16x32_bf16 v[40:43], v[150:153], v[182:185], 0
	v_mfma_f32_16x16x32_bf16 v[28:31], v[138:141], v[190:193], 0
	v_mfma_f32_16x16x32_bf16 v[24:27], v[150:153], v[190:193], 0
	v_mfma_f32_16x16x32_bf16 v[12:15], v[138:141], v[198:201], 0
	v_mfma_f32_16x16x32_bf16 v[8:11], v[150:153], v[198:201], 0
	v_mfma_f32_16x16x32_bf16 v[60:63], v[146:149], v[178:181], v[60:63]
	v_mfma_f32_16x16x32_bf16 v[56:59], v[154:157], v[178:181], v[56:59]
	v_mfma_f32_16x16x32_bf16 v[44:47], v[146:149], v[186:189], v[44:47]
	v_mfma_f32_16x16x32_bf16 v[40:43], v[154:157], v[186:189], v[40:43]
	v_mfma_f32_16x16x32_bf16 v[28:31], v[146:149], v[194:197], v[28:31]
	v_mfma_f32_16x16x32_bf16 v[24:27], v[154:157], v[194:197], v[24:27]
	v_mfma_f32_16x16x32_bf16 v[12:15], v[146:149], v[202:205], v[12:15]
	v_mfma_f32_16x16x32_bf16 v[8:11], v[154:157], v[202:205], v[8:11]
	s_setprio 0
	s_setprio 1
	v_mfma_f32_16x16x32_bf16 v[52:55], v[158:161], v[174:177], 0
	v_mfma_f32_16x16x32_bf16 v[48:51], v[166:169], v[174:177], 0
	v_mfma_f32_16x16x32_bf16 v[36:39], v[158:161], v[182:185], 0
	v_mfma_f32_16x16x32_bf16 v[32:35], v[166:169], v[182:185], 0
	v_mfma_f32_16x16x32_bf16 v[20:23], v[158:161], v[190:193], 0
	v_mfma_f32_16x16x32_bf16 v[16:19], v[166:169], v[190:193], 0
	v_mfma_f32_16x16x32_bf16 v[4:7], v[158:161], v[198:201], 0
	v_mfma_f32_16x16x32_bf16 v[0:3], v[166:169], v[198:201], 0
	v_mfma_f32_16x16x32_bf16 v[52:55], v[162:165], v[178:181], v[52:55]
	v_mfma_f32_16x16x32_bf16 v[48:51], v[170:173], v[178:181], v[48:51]
	v_mfma_f32_16x16x32_bf16 v[36:39], v[162:165], v[186:189], v[36:39]
	v_mfma_f32_16x16x32_bf16 v[32:35], v[170:173], v[186:189], v[32:35]
	v_mfma_f32_16x16x32_bf16 v[20:23], v[162:165], v[194:197], v[20:23]
	v_mfma_f32_16x16x32_bf16 v[16:19], v[170:173], v[194:197], v[16:19]
	v_mfma_f32_16x16x32_bf16 v[4:7], v[162:165], v[202:205], v[4:7]
	v_mfma_f32_16x16x32_bf16 v[0:3], v[170:173], v[202:205], v[0:3]
	s_setprio 0
	s_barrier
	s_branch .Lzmid_2

.LBB0_1163:
	s_ashr_i32 s23, s22, 31
	s_lshl_b64 s[24:25], s[22:23], 19
	s_add_u32 s24, s42, s24
	s_addc_u32 s25, s43, s25
	s_and_b64 s[26:27], s[4:5], exec
	s_cselect_b32 s23, s25, s35
	s_cselect_b32 s56, s24, s34
	s_ashr_i32 s21, s20, 31
	s_lshl_b64 s[26:27], s[20:21], 19
	s_add_u32 s26, s44, s26
	s_addc_u32 s27, s45, s27
	s_and_b64 s[36:37], s[4:5], exec
	s_cselect_b32 s21, s27, s31
	s_cselect_b32 s57, s26, s30
	s_add_u32 s58, s30, 0x100
	s_addc_u32 s59, s31, 0
	s_add_u32 s30, s34, 0x40080
	s_addc_u32 s31, s35, 0
	s_mov_b32 s60, -2
	s_cmp_lt_u32 s54, 2
	s_cbranch_scc1 .Lzfirst_3
	s_add_u32 s34, s30, 0xfffc0080
	s_addc_u32 s35, s31, -1
	s_add_i32 s61, 0, 0x10000
	s_cmp_eq_u32 s60, 12
	s_cselect_b32 s37, s23, s35
	s_cselect_b32 s36, s56, s34
	s_cselect_b32 s35, s21, s59
	s_cselect_b32 s34, s57, s58
	s_add_i32 s64, 0, 0x14000
	v_add_u32_e32 v140, s61, v174
	v_add_u32_e32 v166, s64, v174
	ds_read_b128 v[128:131], v140
	ds_read_b128 v[132:135], v140 offset:1024
	ds_read_b128 v[136:139], v140 offset:2048
	ds_read_b128 v[140:143], v140 offset:3072
	ds_read_b128 v[154:157], v166
	ds_read_b128 v[158:161], v166 offset:1024
	ds_read_b128 v[162:165], v166 offset:2048
	ds_read_b128 v[166:169], v166 offset:3072
	v_lshl_add_u64 v[204:205], s[30:31], 0, v[152:153]
	s_add_i32 m0, s29, 0xc000
	ds_read_b128 v[170:173], v175
	ds_read_b128 v[176:179], v175 offset:1024
	ds_read_b128 v[180:183], v175 offset:2048
	ds_read_b128 v[184:187], v175 offset:3072
	ds_read_b128 v[188:191], v175 offset:4096
	ds_read_b128 v[192:195], v175 offset:5120
	ds_read_b128 v[196:199], v175 offset:6144
	ds_read_b128 v[200:203], v175 offset:7168
	global_load_lds_dwordx4 v[204:205], off
	v_lshl_add_u64 v[204:205], s[30:31], 0, v[150:151]
	s_add_i32 m0, s29, 0xe000
	s_nop 0
	global_load_lds_dwordx4 v[204:205], off
	s_waitcnt vmcnt(40)
	s_waitcnt lgkmcnt(0)
	s_barrier
	s_setprio 1
	s_waitcnt lgkmcnt(0)
	v_mfma_f32_16x16x32_bf16 v[124:127], v[128:131], v[170:173], 0
	v_mfma_f32_16x16x32_bf16 v[120:123], v[136:139], v[170:173], 0
	v_mfma_f32_16x16x32_bf16 v[108:111], v[128:131], v[180:183], 0
	v_mfma_f32_16x16x32_bf16 v[104:107], v[136:139], v[180:183], 0
	v_mfma_f32_16x16x32_bf16 v[92:95], v[128:131], v[188:191], 0
	v_mfma_f32_16x16x32_bf16 v[88:91], v[136:139], v[188:191], 0
	v_mfma_f32_16x16x32_bf16 v[80:83], v[128:131], v[196:199], 0
	v_mfma_f32_16x16x32_bf16 v[72:75], v[136:139], v[196:199], 0
	v_mfma_f32_16x16x32_bf16 v[124:127], v[132:135], v[176:179], v[124:127]
	v_mfma_f32_16x16x32_bf16 v[120:123], v[140:143], v[176:179], v[120:123]
	v_mfma_f32_16x16x32_bf16 v[108:111], v[132:135], v[184:187], v[108:111]
	v_mfma_f32_16x16x32_bf16 v[104:107], v[140:143], v[184:187], v[104:107]
	v_mfma_f32_16x16x32_bf16 v[92:95], v[132:135], v[192:195], v[92:95]
	v_mfma_f32_16x16x32_bf16 v[88:91], v[140:143], v[192:195], v[88:91]
	v_mfma_f32_16x16x32_bf16 v[80:83], v[132:135], v[200:203], v[80:83]
	v_mfma_f32_16x16x32_bf16 v[72:75], v[140:143], v[200:203], v[72:75]
	s_setprio 0
	s_setprio 1
	v_mfma_f32_16x16x32_bf16 v[116:119], v[154:157], v[170:173], 0
	v_mfma_f32_16x16x32_bf16 v[112:115], v[162:165], v[170:173], 0
	v_mfma_f32_16x16x32_bf16 v[100:103], v[154:157], v[180:183], 0
	v_mfma_f32_16x16x32_bf16 v[96:99], v[162:165], v[180:183], 0
	v_mfma_f32_16x16x32_bf16 v[84:87], v[154:157], v[188:191], 0
	v_mfma_f32_16x16x32_bf16 v[76:79], v[162:165], v[188:191], 0
	v_mfma_f32_16x16x32_bf16 v[68:71], v[154:157], v[196:199], 0
	v_mfma_f32_16x16x32_bf16 v[64:67], v[162:165], v[196:199], 0
	v_mfma_f32_16x16x32_bf16 v[116:119], v[158:161], v[176:179], v[116:119]
	v_mfma_f32_16x16x32_bf16 v[112:115], v[166:169], v[176:179], v[112:115]
	v_mfma_f32_16x16x32_bf16 v[100:103], v[158:161], v[184:187], v[100:103]
	v_mfma_f32_16x16x32_bf16 v[96:99], v[166:169], v[184:187], v[96:99]
	v_mfma_f32_16x16x32_bf16 v[84:87], v[158:161], v[192:195], v[84:87]
	v_mfma_f32_16x16x32_bf16 v[76:79], v[166:169], v[192:195], v[76:79]
	v_mfma_f32_16x16x32_bf16 v[68:71], v[158:161], v[200:203], v[68:71]
	v_mfma_f32_16x16x32_bf16 v[64:67], v[166:169], v[200:203], v[64:67]
	s_setprio 0
	s_barrier
	s_add_i32 s61, s61, s41
	v_lshl_add_u64 v[204:205], s[34:35], 0, v[232:233]
	s_mov_b32 m0, s61
	ds_read_b128 v[170:173], v175 offset:16384
	ds_read_b128 v[176:179], v175 offset:17408
	ds_read_b128 v[180:183], v175 offset:18432
	ds_read_b128 v[184:187], v175 offset:19456
	ds_read_b128 v[188:191], v175 offset:20480
	ds_read_b128 v[192:195], v175 offset:21504
	ds_read_b128 v[196:199], v175 offset:22528
	ds_read_b128 v[200:203], v175 offset:23552
	global_load_lds_dwordx4 v[204:205], off
	s_add_i32 m0, s61, 0x2000
	s_add_u32 s62, s34, 0x40000
	v_lshl_add_u64 v[206:207], s[34:35], 0, v[148:149]
	s_addc_u32 s63, s35, 0
	s_add_i32 s61, s64, s41
	global_load_lds_dwordx4 v[206:207], off
	v_lshl_add_u64 v[208:209], s[62:63], 0, v[232:233]
	s_mov_b32 m0, s61
	v_lshl_add_u64 v[210:211], s[36:37], 0, v[146:147]
	global_load_lds_dwordx4 v[208:209], off
	v_lshl_add_u64 v[208:209], s[62:63], 0, v[148:149]
	s_add_i32 m0, s61, 0x2000
	s_nop 0
	global_load_lds_dwordx4 v[208:209], off
	v_lshl_add_u64 v[208:209], s[36:37], 0, v[144:145]
	s_waitcnt vmcnt(38)
	s_waitcnt lgkmcnt(0)
	s_barrier
	s_setprio 1
	s_waitcnt lgkmcnt(0)
	v_mfma_f32_16x16x32_bf16 v[60:63], v[128:131], v[170:173], 0
	v_mfma_f32_16x16x32_bf16 v[56:59], v[136:139], v[170:173], 0
	v_mfma_f32_16x16x32_bf16 v[48:51], v[128:131], v[180:183], 0
	v_mfma_f32_16x16x32_bf16 v[40:43], v[136:139], v[180:183], 0
	v_mfma_f32_16x16x32_bf16 v[28:31], v[128:131], v[188:191], 0
	v_mfma_f32_16x16x32_bf16 v[24:27], v[136:139], v[188:191], 0
	v_mfma_f32_16x16x32_bf16 v[16:19], v[128:131], v[196:199], 0
	v_mfma_f32_16x16x32_bf16 v[8:11], v[136:139], v[196:199], 0
	v_mfma_f32_16x16x32_bf16 v[60:63], v[132:135], v[176:179], v[60:63]
	v_mfma_f32_16x16x32_bf16 v[56:59], v[140:143], v[176:179], v[56:59]
	v_mfma_f32_16x16x32_bf16 v[48:51], v[132:135], v[184:187], v[48:51]
	v_mfma_f32_16x16x32_bf16 v[40:43], v[140:143], v[184:187], v[40:43]
	v_mfma_f32_16x16x32_bf16 v[28:31], v[132:135], v[192:195], v[28:31]
	v_mfma_f32_16x16x32_bf16 v[24:27], v[140:143], v[192:195], v[24:27]
	v_mfma_f32_16x16x32_bf16 v[16:19], v[132:135], v[200:203], v[16:19]
	v_mfma_f32_16x16x32_bf16 v[8:11], v[140:143], v[200:203], v[8:11]
	s_setprio 0
	s_setprio 1
	v_mfma_f32_16x16x32_bf16 v[52:55], v[154:157], v[170:173], 0
	v_mfma_f32_16x16x32_bf16 v[44:47], v[162:165], v[170:173], 0
	v_mfma_f32_16x16x32_bf16 v[36:39], v[154:157], v[180:183], 0
	v_mfma_f32_16x16x32_bf16 v[32:35], v[162:165], v[180:183], 0
	v_mfma_f32_16x16x32_bf16 v[20:23], v[154:157], v[188:191], 0
	v_mfma_f32_16x16x32_bf16 v[12:15], v[162:165], v[188:191], 0
	v_mfma_f32_16x16x32_bf16 v[4:7], v[154:157], v[196:199], 0
	v_mfma_f32_16x16x32_bf16 v[0:3], v[162:165], v[196:199], 0
	v_mfma_f32_16x16x32_bf16 v[52:55], v[158:161], v[176:179], v[52:55]
	v_mfma_f32_16x16x32_bf16 v[44:47], v[166:169], v[176:179], v[44:47]
	v_mfma_f32_16x16x32_bf16 v[36:39], v[158:161], v[184:187], v[36:39]
	v_mfma_f32_16x16x32_bf16 v[32:35], v[166:169], v[184:187], v[32:35]
	v_mfma_f32_16x16x32_bf16 v[20:23], v[158:161], v[192:195], v[20:23]
	v_mfma_f32_16x16x32_bf16 v[12:15], v[166:169], v[192:195], v[12:15]
	v_mfma_f32_16x16x32_bf16 v[4:7], v[158:161], v[200:203], v[4:7]
	v_mfma_f32_16x16x32_bf16 v[0:3], v[166:169], v[200:203], v[0:3]
	s_setprio 0
	s_barrier
	s_branch .Lzmid_3
.Lzfirst_3:
	s_add_u32 s34, s30, 0xfffc0080
	s_addc_u32 s35, s31, -1
	s_add_i32 s61, 0, 0x10000
	s_cmp_eq_u32 s60, 12
	s_cselect_b32 s37, s23, s35
	s_cselect_b32 s36, s56, s34
	s_cselect_b32 s35, s21, s59
	s_cselect_b32 s34, s57, s58
	s_add_i32 s64, 0, 0x14000
	v_add_u32_e32 v140, s61, v174
	v_add_u32_e32 v166, s64, v174
	ds_read_b128 v[128:131], v140
	ds_read_b128 v[132:135], v140 offset:1024
	ds_read_b128 v[136:139], v140 offset:2048
	ds_read_b128 v[140:143], v140 offset:3072
	ds_read_b128 v[154:157], v166
	ds_read_b128 v[158:161], v166 offset:1024
	ds_read_b128 v[162:165], v166 offset:2048
	ds_read_b128 v[166:169], v166 offset:3072
	v_lshl_add_u64 v[204:205], s[30:31], 0, v[152:153]
	s_add_i32 m0, s29, 0xc000
	ds_read_b128 v[170:173], v175
	ds_read_b128 v[176:179], v175 offset:1024
	ds_read_b128 v[180:183], v175 offset:2048
	ds_read_b128 v[184:187], v175 offset:3072
	ds_read_b128 v[188:191], v175 offset:4096
	ds_read_b128 v[192:195], v175 offset:5120
	ds_read_b128 v[196:199], v175 offset:6144
	ds_read_b128 v[200:203], v175 offset:7168
	global_load_lds_dwordx4 v[204:205], off
	v_lshl_add_u64 v[204:205], s[30:31], 0, v[150:151]
	s_add_i32 m0, s29, 0xe000
	s_nop 0
	global_load_lds_dwordx4 v[204:205], off
	s_waitcnt vmcnt(8)
	s_waitcnt lgkmcnt(0)
	s_barrier
	s_setprio 1
	s_waitcnt lgkmcnt(0)
	v_mfma_f32_16x16x32_bf16 v[124:127], v[128:131], v[170:173], 0
	v_mfma_f32_16x16x32_bf16 v[120:123], v[136:139], v[170:173], 0
	v_mfma_f32_16x16x32_bf16 v[108:111], v[128:131], v[180:183], 0
	v_mfma_f32_16x16x32_bf16 v[104:107], v[136:139], v[180:183], 0
	v_mfma_f32_16x16x32_bf16 v[92:95], v[128:131], v[188:191], 0
	v_mfma_f32_16x16x32_bf16 v[88:91], v[136:139], v[188:191], 0
	v_mfma_f32_16x16x32_bf16 v[80:83], v[128:131], v[196:199], 0
	v_mfma_f32_16x16x32_bf16 v[72:75], v[136:139], v[196:199], 0
	v_mfma_f32_16x16x32_bf16 v[124:127], v[132:135], v[176:179], v[124:127]
	v_mfma_f32_16x16x32_bf16 v[120:123], v[140:143], v[176:179], v[120:123]
	v_mfma_f32_16x16x32_bf16 v[108:111], v[132:135], v[184:187], v[108:111]
	v_mfma_f32_16x16x32_bf16 v[104:107], v[140:143], v[184:187], v[104:107]
	v_mfma_f32_16x16x32_bf16 v[92:95], v[132:135], v[192:195], v[92:95]
	v_mfma_f32_16x16x32_bf16 v[88:91], v[140:143], v[192:195], v[88:91]
	v_mfma_f32_16x16x32_bf16 v[80:83], v[132:135], v[200:203], v[80:83]
	v_mfma_f32_16x16x32_bf16 v[72:75], v[140:143], v[200:203], v[72:75]
	s_setprio 0
	s_setprio 1
	v_mfma_f32_16x16x32_bf16 v[116:119], v[154:157], v[170:173], 0
	v_mfma_f32_16x16x32_bf16 v[112:115], v[162:165], v[170:173], 0
	v_mfma_f32_16x16x32_bf16 v[100:103], v[154:157], v[180:183], 0
	v_mfma_f32_16x16x32_bf16 v[96:99], v[162:165], v[180:183], 0
	v_mfma_f32_16x16x32_bf16 v[84:87], v[154:157], v[188:191], 0
	v_mfma_f32_16x16x32_bf16 v[76:79], v[162:165], v[188:191], 0
	v_mfma_f32_16x16x32_bf16 v[68:71], v[154:157], v[196:199], 0
	v_mfma_f32_16x16x32_bf16 v[64:67], v[162:165], v[196:199], 0
	v_mfma_f32_16x16x32_bf16 v[116:119], v[158:161], v[176:179], v[116:119]
	v_mfma_f32_16x16x32_bf16 v[112:115], v[166:169], v[176:179], v[112:115]
	v_mfma_f32_16x16x32_bf16 v[100:103], v[158:161], v[184:187], v[100:103]
	v_mfma_f32_16x16x32_bf16 v[96:99], v[166:169], v[184:187], v[96:99]
	v_mfma_f32_16x16x32_bf16 v[84:87], v[158:161], v[192:195], v[84:87]
	v_mfma_f32_16x16x32_bf16 v[76:79], v[166:169], v[192:195], v[76:79]
	v_mfma_f32_16x16x32_bf16 v[68:71], v[158:161], v[200:203], v[68:71]
	v_mfma_f32_16x16x32_bf16 v[64:67], v[166:169], v[200:203], v[64:67]
	s_setprio 0
	s_barrier
	s_add_i32 s61, s61, s41
	v_lshl_add_u64 v[204:205], s[34:35], 0, v[232:233]
	s_mov_b32 m0, s61
	ds_read_b128 v[170:173], v175 offset:16384
	ds_read_b128 v[176:179], v175 offset:17408
	ds_read_b128 v[180:183], v175 offset:18432
	ds_read_b128 v[184:187], v175 offset:19456
	ds_read_b128 v[188:191], v175 offset:20480
	ds_read_b128 v[192:195], v175 offset:21504
	ds_read_b128 v[196:199], v175 offset:22528
	ds_read_b128 v[200:203], v175 offset:23552
	global_load_lds_dwordx4 v[204:205], off
	s_add_i32 m0, s61, 0x2000
	s_add_u32 s62, s34, 0x40000
	v_lshl_add_u64 v[206:207], s[34:35], 0, v[148:149]
	s_addc_u32 s63, s35, 0
	s_add_i32 s61, s64, s41
	global_load_lds_dwordx4 v[206:207], off
	v_lshl_add_u64 v[208:209], s[62:63], 0, v[232:233]
	s_mov_b32 m0, s61
	v_lshl_add_u64 v[210:211], s[36:37], 0, v[146:147]
	global_load_lds_dwordx4 v[208:209], off
	v_lshl_add_u64 v[208:209], s[62:63], 0, v[148:149]
	s_add_i32 m0, s61, 0x2000
	s_nop 0
	global_load_lds_dwordx4 v[208:209], off
	v_lshl_add_u64 v[208:209], s[36:37], 0, v[144:145]
	s_waitcnt vmcnt(6)
	s_waitcnt lgkmcnt(0)
	s_barrier
	s_setprio 1
	s_waitcnt lgkmcnt(0)
	v_mfma_f32_16x16x32_bf16 v[60:63], v[128:131], v[170:173], 0
	v_mfma_f32_16x16x32_bf16 v[56:59], v[136:139], v[170:173], 0
	v_mfma_f32_16x16x32_bf16 v[48:51], v[128:131], v[180:183], 0
	v_mfma_f32_16x16x32_bf16 v[40:43], v[136:139], v[180:183], 0
	v_mfma_f32_16x16x32_bf16 v[28:31], v[128:131], v[188:191], 0
	v_mfma_f32_16x16x32_bf16 v[24:27], v[136:139], v[188:191], 0
	v_mfma_f32_16x16x32_bf16 v[16:19], v[128:131], v[196:199], 0
	v_mfma_f32_16x16x32_bf16 v[8:11], v[136:139], v[196:199], 0
	v_mfma_f32_16x16x32_bf16 v[60:63], v[132:135], v[176:179], v[60:63]
	v_mfma_f32_16x16x32_bf16 v[56:59], v[140:143], v[176:179], v[56:59]
	v_mfma_f32_16x16x32_bf16 v[48:51], v[132:135], v[184:187], v[48:51]
	v_mfma_f32_16x16x32_bf16 v[40:43], v[140:143], v[184:187], v[40:43]
	v_mfma_f32_16x16x32_bf16 v[28:31], v[132:135], v[192:195], v[28:31]
	v_mfma_f32_16x16x32_bf16 v[24:27], v[140:143], v[192:195], v[24:27]
	v_mfma_f32_16x16x32_bf16 v[16:19], v[132:135], v[200:203], v[16:19]
	v_mfma_f32_16x16x32_bf16 v[8:11], v[140:143], v[200:203], v[8:11]
	s_setprio 0
	s_setprio 1
	v_mfma_f32_16x16x32_bf16 v[52:55], v[154:157], v[170:173], 0
	v_mfma_f32_16x16x32_bf16 v[44:47], v[162:165], v[170:173], 0
	v_mfma_f32_16x16x32_bf16 v[36:39], v[154:157], v[180:183], 0
	v_mfma_f32_16x16x32_bf16 v[32:35], v[162:165], v[180:183], 0
	v_mfma_f32_16x16x32_bf16 v[20:23], v[154:157], v[188:191], 0
	v_mfma_f32_16x16x32_bf16 v[12:15], v[162:165], v[188:191], 0
	v_mfma_f32_16x16x32_bf16 v[4:7], v[154:157], v[196:199], 0
	v_mfma_f32_16x16x32_bf16 v[0:3], v[162:165], v[196:199], 0
	v_mfma_f32_16x16x32_bf16 v[52:55], v[158:161], v[176:179], v[52:55]
	v_mfma_f32_16x16x32_bf16 v[44:47], v[166:169], v[176:179], v[44:47]
	v_mfma_f32_16x16x32_bf16 v[36:39], v[158:161], v[184:187], v[36:39]
	v_mfma_f32_16x16x32_bf16 v[32:35], v[166:169], v[184:187], v[32:35]
	v_mfma_f32_16x16x32_bf16 v[20:23], v[158:161], v[192:195], v[20:23]
	v_mfma_f32_16x16x32_bf16 v[12:15], v[166:169], v[192:195], v[12:15]
	v_mfma_f32_16x16x32_bf16 v[4:7], v[158:161], v[200:203], v[4:7]
	v_mfma_f32_16x16x32_bf16 v[0:3], v[166:169], v[200:203], v[0:3]
	s_setprio 0
	s_barrier
	s_branch .Lzmid_3

.LBB0_1306:
	s_ashr_i32 s17, s16, 31
	s_lshl_b64 s[18:19], s[16:17], 19
	s_add_u32 s18, s34, s18
	s_addc_u32 s19, s35, s19
	s_and_b64 s[20:21], s[4:5], exec
	s_cselect_b32 s7, s19, s27
	s_cselect_b32 s17, s18, s26
	s_ashr_i32 s15, s14, 31
	s_lshl_b64 s[20:21], s[14:15], 19
	s_add_u32 s20, s36, s20
	s_addc_u32 s21, s37, s21
	s_and_b64 s[28:29], s[4:5], exec
	s_cselect_b32 s15, s21, s25
	s_cselect_b32 s23, s20, s24
	s_add_u32 s50, s24, 0x100
	s_addc_u32 s51, s25, 0
	s_add_u32 s24, s26, 0x40080
	s_addc_u32 s25, s27, 0
	s_mov_b32 s52, -2
	s_cmp_lt_u32 s49, 2
	s_cbranch_scc1 .Lzfirst_4
	s_add_u32 s26, s24, 0xfffc0080
	s_addc_u32 s27, s25, -1
	s_add_i32 s53, 0, 0x10000
	s_cmp_eq_u32 s52, 12
	s_cselect_b32 s29, s7, s27
	s_cselect_b32 s28, s17, s26
	v_add_u32_e32 v142, s53, v144
	s_cselect_b32 s27, s15, s51
	s_cselect_b32 s26, s23, s50
	s_add_i32 s56, 0, 0x14000
	ds_read_b128 v[138:141], v142
	ds_read_b128 v[146:149], v142 offset:1024
	ds_read_b128 v[150:153], v142 offset:2048
	ds_read_b128 v[154:157], v142 offset:3072
	v_add_u32_e32 v142, s56, v144
	ds_read_b128 v[158:161], v142
	ds_read_b128 v[162:165], v142 offset:1024
	ds_read_b128 v[166:169], v142 offset:2048
	ds_read_b128 v[170:173], v142 offset:3072
	v_lshl_add_u64 v[142:143], s[24:25], 0, v[136:137]
	s_add_i32 m0, s39, 0xc000
	ds_read_b128 v[174:177], v145
	ds_read_b128 v[178:181], v145 offset:1024
	ds_read_b128 v[182:185], v145 offset:2048
	ds_read_b128 v[186:189], v145 offset:3072
	ds_read_b128 v[190:193], v145 offset:4096
	ds_read_b128 v[194:197], v145 offset:5120
	ds_read_b128 v[198:201], v145 offset:6144
	ds_read_b128 v[202:205], v145 offset:7168
	global_load_lds_dwordx4 v[142:143], off
	v_lshl_add_u64 v[142:143], s[24:25], 0, v[134:135]
	s_add_i32 m0, s39, 0xe000
	s_nop 0
	global_load_lds_dwordx4 v[142:143], off
	s_waitcnt vmcnt(24)
	s_waitcnt lgkmcnt(0)
	s_barrier
	s_setprio 1
	s_waitcnt lgkmcnt(0)
	v_mfma_f32_16x16x32_bf16 v[124:127], v[138:141], v[174:177], 0
	v_mfma_f32_16x16x32_bf16 v[120:123], v[150:153], v[174:177], 0
	v_mfma_f32_16x16x32_bf16 v[108:111], v[138:141], v[182:185], 0
	v_mfma_f32_16x16x32_bf16 v[104:107], v[150:153], v[182:185], 0
	v_mfma_f32_16x16x32_bf16 v[92:95], v[138:141], v[190:193], 0
	v_mfma_f32_16x16x32_bf16 v[88:91], v[150:153], v[190:193], 0
	v_mfma_f32_16x16x32_bf16 v[76:79], v[138:141], v[198:201], 0
	v_mfma_f32_16x16x32_bf16 v[72:75], v[150:153], v[198:201], 0
	v_mfma_f32_16x16x32_bf16 v[124:127], v[146:149], v[178:181], v[124:127]
	v_mfma_f32_16x16x32_bf16 v[120:123], v[154:157], v[178:181], v[120:123]
	v_mfma_f32_16x16x32_bf16 v[108:111], v[146:149], v[186:189], v[108:111]
	v_mfma_f32_16x16x32_bf16 v[104:107], v[154:157], v[186:189], v[104:107]
	v_mfma_f32_16x16x32_bf16 v[92:95], v[146:149], v[194:197], v[92:95]
	v_mfma_f32_16x16x32_bf16 v[88:91], v[154:157], v[194:197], v[88:91]
	v_mfma_f32_16x16x32_bf16 v[76:79], v[146:149], v[202:205], v[76:79]
	v_mfma_f32_16x16x32_bf16 v[72:75], v[154:157], v[202:205], v[72:75]
	s_setprio 0
	s_setprio 1
	v_mfma_f32_16x16x32_bf16 v[116:119], v[158:161], v[174:177], 0
	v_mfma_f32_16x16x32_bf16 v[112:115], v[166:169], v[174:177], 0
	v_mfma_f32_16x16x32_bf16 v[100:103], v[158:161], v[182:185], 0
	v_mfma_f32_16x16x32_bf16 v[96:99], v[166:169], v[182:185], 0
	v_mfma_f32_16x16x32_bf16 v[84:87], v[158:161], v[190:193], 0
	v_mfma_f32_16x16x32_bf16 v[80:83], v[166:169], v[190:193], 0
	v_mfma_f32_16x16x32_bf16 v[68:71], v[158:161], v[198:201], 0
	v_mfma_f32_16x16x32_bf16 v[64:67], v[166:169], v[198:201], 0
	v_mfma_f32_16x16x32_bf16 v[116:119], v[162:165], v[178:181], v[116:119]
	v_mfma_f32_16x16x32_bf16 v[112:115], v[170:173], v[178:181], v[112:115]
	v_mfma_f32_16x16x32_bf16 v[100:103], v[162:165], v[186:189], v[100:103]
	v_mfma_f32_16x16x32_bf16 v[96:99], v[170:173], v[186:189], v[96:99]
	v_mfma_f32_16x16x32_bf16 v[84:87], v[162:165], v[194:197], v[84:87]
	v_mfma_f32_16x16x32_bf16 v[80:83], v[170:173], v[194:197], v[80:83]
	v_mfma_f32_16x16x32_bf16 v[68:71], v[162:165], v[202:205], v[68:71]
	v_mfma_f32_16x16x32_bf16 v[64:67], v[170:173], v[202:205], v[64:67]
	s_setprio 0
	s_barrier
	s_add_i32 s53, s53, s38
	v_lshl_add_u64 v[142:143], s[26:27], 0, v[232:233]
	s_mov_b32 m0, s53
	ds_read_b128 v[174:177], v145 offset:16384
	ds_read_b128 v[178:181], v145 offset:17408
	ds_read_b128 v[182:185], v145 offset:18432
	ds_read_b128 v[186:189], v145 offset:19456
	ds_read_b128 v[190:193], v145 offset:20480
	ds_read_b128 v[194:197], v145 offset:21504
	ds_read_b128 v[198:201], v145 offset:22528
	ds_read_b128 v[202:205], v145 offset:23552
	global_load_lds_dwordx4 v[142:143], off
	s_add_i32 m0, s53, 0x2000
	s_add_u32 s54, s26, 0x40000
	v_lshl_add_u64 v[206:207], s[26:27], 0, v[132:133]
	s_addc_u32 s55, s27, 0
	s_add_i32 s53, s56, s38
	global_load_lds_dwordx4 v[206:207], off
	v_lshl_add_u64 v[208:209], s[54:55], 0, v[232:233]
	s_mov_b32 m0, s53
	v_lshl_add_u64 v[210:211], s[28:29], 0, v[130:131]
	global_load_lds_dwordx4 v[208:209], off
	v_lshl_add_u64 v[208:209], s[54:55], 0, v[132:133]
	s_add_i32 m0, s53, 0x2000
	s_nop 0
	global_load_lds_dwordx4 v[208:209], off
	v_lshl_add_u64 v[208:209], s[28:29], 0, v[128:129]
	s_waitcnt vmcnt(22)
	s_waitcnt lgkmcnt(0)
	s_barrier
	s_setprio 1
	s_waitcnt lgkmcnt(0)
	v_mfma_f32_16x16x32_bf16 v[60:63], v[138:141], v[174:177], 0
	v_mfma_f32_16x16x32_bf16 v[56:59], v[150:153], v[174:177], 0
	v_mfma_f32_16x16x32_bf16 v[44:47], v[138:141], v[182:185], 0
	v_mfma_f32_16x16x32_bf16 v[40:43], v[150:153], v[182:185], 0
	v_mfma_f32_16x16x32_bf16 v[28:31], v[138:141], v[190:193], 0
	v_mfma_f32_16x16x32_bf16 v[24:27], v[150:153], v[190:193], 0
	v_mfma_f32_16x16x32_bf16 v[12:15], v[138:141], v[198:201], 0
	v_mfma_f32_16x16x32_bf16 v[8:11], v[150:153], v[198:201], 0
	v_mfma_f32_16x16x32_bf16 v[60:63], v[146:149], v[178:181], v[60:63]
	v_mfma_f32_16x16x32_bf16 v[56:59], v[154:157], v[178:181], v[56:59]
	v_mfma_f32_16x16x32_bf16 v[44:47], v[146:149], v[186:189], v[44:47]
	v_mfma_f32_16x16x32_bf16 v[40:43], v[154:157], v[186:189], v[40:43]
	v_mfma_f32_16x16x32_bf16 v[28:31], v[146:149], v[194:197], v[28:31]
	v_mfma_f32_16x16x32_bf16 v[24:27], v[154:157], v[194:197], v[24:27]
	v_mfma_f32_16x16x32_bf16 v[12:15], v[146:149], v[202:205], v[12:15]
	v_mfma_f32_16x16x32_bf16 v[8:11], v[154:157], v[202:205], v[8:11]
	s_setprio 0
	s_setprio 1
	v_mfma_f32_16x16x32_bf16 v[52:55], v[158:161], v[174:177], 0
	v_mfma_f32_16x16x32_bf16 v[48:51], v[166:169], v[174:177], 0
	v_mfma_f32_16x16x32_bf16 v[36:39], v[158:161], v[182:185], 0
	v_mfma_f32_16x16x32_bf16 v[32:35], v[166:169], v[182:185], 0
	v_mfma_f32_16x16x32_bf16 v[20:23], v[158:161], v[190:193], 0
	v_mfma_f32_16x16x32_bf16 v[16:19], v[166:169], v[190:193], 0
	v_mfma_f32_16x16x32_bf16 v[4:7], v[158:161], v[198:201], 0
	v_mfma_f32_16x16x32_bf16 v[0:3], v[166:169], v[198:201], 0
	v_mfma_f32_16x16x32_bf16 v[52:55], v[162:165], v[178:181], v[52:55]
	v_mfma_f32_16x16x32_bf16 v[48:51], v[170:173], v[178:181], v[48:51]
	v_mfma_f32_16x16x32_bf16 v[36:39], v[162:165], v[186:189], v[36:39]
	v_mfma_f32_16x16x32_bf16 v[32:35], v[170:173], v[186:189], v[32:35]
	v_mfma_f32_16x16x32_bf16 v[20:23], v[162:165], v[194:197], v[20:23]
	v_mfma_f32_16x16x32_bf16 v[16:19], v[170:173], v[194:197], v[16:19]
	v_mfma_f32_16x16x32_bf16 v[4:7], v[162:165], v[202:205], v[4:7]
	v_mfma_f32_16x16x32_bf16 v[0:3], v[170:173], v[202:205], v[0:3]
	s_setprio 0
	s_barrier
	s_branch .Lzmid_4
.Lzfirst_4:
	s_add_u32 s26, s24, 0xfffc0080
	s_addc_u32 s27, s25, -1
	s_add_i32 s53, 0, 0x10000
	s_cmp_eq_u32 s52, 12
	s_cselect_b32 s29, s7, s27
	s_cselect_b32 s28, s17, s26
	v_add_u32_e32 v142, s53, v144
	s_cselect_b32 s27, s15, s51
	s_cselect_b32 s26, s23, s50
	s_add_i32 s56, 0, 0x14000
	ds_read_b128 v[138:141], v142
	ds_read_b128 v[146:149], v142 offset:1024
	ds_read_b128 v[150:153], v142 offset:2048
	ds_read_b128 v[154:157], v142 offset:3072
	v_add_u32_e32 v142, s56, v144
	ds_read_b128 v[158:161], v142
	ds_read_b128 v[162:165], v142 offset:1024
	ds_read_b128 v[166:169], v142 offset:2048
	ds_read_b128 v[170:173], v142 offset:3072
	v_lshl_add_u64 v[142:143], s[24:25], 0, v[136:137]
	s_add_i32 m0, s39, 0xc000
	ds_read_b128 v[174:177], v145
	ds_read_b128 v[178:181], v145 offset:1024
	ds_read_b128 v[182:185], v145 offset:2048
	ds_read_b128 v[186:189], v145 offset:3072
	ds_read_b128 v[190:193], v145 offset:4096
	ds_read_b128 v[194:197], v145 offset:5120
	ds_read_b128 v[198:201], v145 offset:6144
	ds_read_b128 v[202:205], v145 offset:7168
	global_load_lds_dwordx4 v[142:143], off
	v_lshl_add_u64 v[142:143], s[24:25], 0, v[134:135]
	s_add_i32 m0, s39, 0xe000
	s_nop 0
	global_load_lds_dwordx4 v[142:143], off
	s_waitcnt vmcnt(8)
	s_waitcnt lgkmcnt(0)
	s_barrier
	s_setprio 1
	s_waitcnt lgkmcnt(0)
	v_mfma_f32_16x16x32_bf16 v[124:127], v[138:141], v[174:177], 0
	v_mfma_f32_16x16x32_bf16 v[120:123], v[150:153], v[174:177], 0
	v_mfma_f32_16x16x32_bf16 v[108:111], v[138:141], v[182:185], 0
	v_mfma_f32_16x16x32_bf16 v[104:107], v[150:153], v[182:185], 0
	v_mfma_f32_16x16x32_bf16 v[92:95], v[138:141], v[190:193], 0
	v_mfma_f32_16x16x32_bf16 v[88:91], v[150:153], v[190:193], 0
	v_mfma_f32_16x16x32_bf16 v[76:79], v[138:141], v[198:201], 0
	v_mfma_f32_16x16x32_bf16 v[72:75], v[150:153], v[198:201], 0
	v_mfma_f32_16x16x32_bf16 v[124:127], v[146:149], v[178:181], v[124:127]
	v_mfma_f32_16x16x32_bf16 v[120:123], v[154:157], v[178:181], v[120:123]
	v_mfma_f32_16x16x32_bf16 v[108:111], v[146:149], v[186:189], v[108:111]
	v_mfma_f32_16x16x32_bf16 v[104:107], v[154:157], v[186:189], v[104:107]
	v_mfma_f32_16x16x32_bf16 v[92:95], v[146:149], v[194:197], v[92:95]
	v_mfma_f32_16x16x32_bf16 v[88:91], v[154:157], v[194:197], v[88:91]
	v_mfma_f32_16x16x32_bf16 v[76:79], v[146:149], v[202:205], v[76:79]
	v_mfma_f32_16x16x32_bf16 v[72:75], v[154:157], v[202:205], v[72:75]
	s_setprio 0
	s_setprio 1
	v_mfma_f32_16x16x32_bf16 v[116:119], v[158:161], v[174:177], 0
	v_mfma_f32_16x16x32_bf16 v[112:115], v[166:169], v[174:177], 0
	v_mfma_f32_16x16x32_bf16 v[100:103], v[158:161], v[182:185], 0
	v_mfma_f32_16x16x32_bf16 v[96:99], v[166:169], v[182:185], 0
	v_mfma_f32_16x16x32_bf16 v[84:87], v[158:161], v[190:193], 0
	v_mfma_f32_16x16x32_bf16 v[80:83], v[166:169], v[190:193], 0
	v_mfma_f32_16x16x32_bf16 v[68:71], v[158:161], v[198:201], 0
	v_mfma_f32_16x16x32_bf16 v[64:67], v[166:169], v[198:201], 0
	v_mfma_f32_16x16x32_bf16 v[116:119], v[162:165], v[178:181], v[116:119]
	v_mfma_f32_16x16x32_bf16 v[112:115], v[170:173], v[178:181], v[112:115]
	v_mfma_f32_16x16x32_bf16 v[100:103], v[162:165], v[186:189], v[100:103]
	v_mfma_f32_16x16x32_bf16 v[96:99], v[170:173], v[186:189], v[96:99]
	v_mfma_f32_16x16x32_bf16 v[84:87], v[162:165], v[194:197], v[84:87]
	v_mfma_f32_16x16x32_bf16 v[80:83], v[170:173], v[194:197], v[80:83]
	v_mfma_f32_16x16x32_bf16 v[68:71], v[162:165], v[202:205], v[68:71]
	v_mfma_f32_16x16x32_bf16 v[64:67], v[170:173], v[202:205], v[64:67]
	s_setprio 0
	s_barrier
	s_add_i32 s53, s53, s38
	v_lshl_add_u64 v[142:143], s[26:27], 0, v[232:233]
	s_mov_b32 m0, s53
	ds_read_b128 v[174:177], v145 offset:16384
	ds_read_b128 v[178:181], v145 offset:17408
	ds_read_b128 v[182:185], v145 offset:18432
	ds_read_b128 v[186:189], v145 offset:19456
	ds_read_b128 v[190:193], v145 offset:20480
	ds_read_b128 v[194:197], v145 offset:21504
	ds_read_b128 v[198:201], v145 offset:22528
	ds_read_b128 v[202:205], v145 offset:23552
	global_load_lds_dwordx4 v[142:143], off
	s_add_i32 m0, s53, 0x2000
	s_add_u32 s54, s26, 0x40000
	v_lshl_add_u64 v[206:207], s[26:27], 0, v[132:133]
	s_addc_u32 s55, s27, 0
	s_add_i32 s53, s56, s38
	global_load_lds_dwordx4 v[206:207], off
	v_lshl_add_u64 v[208:209], s[54:55], 0, v[232:233]
	s_mov_b32 m0, s53
	v_lshl_add_u64 v[210:211], s[28:29], 0, v[130:131]
	global_load_lds_dwordx4 v[208:209], off
	v_lshl_add_u64 v[208:209], s[54:55], 0, v[132:133]
	s_add_i32 m0, s53, 0x2000
	s_nop 0
	global_load_lds_dwordx4 v[208:209], off
	v_lshl_add_u64 v[208:209], s[28:29], 0, v[128:129]
	s_waitcnt vmcnt(6)
	s_waitcnt lgkmcnt(0)
	s_barrier
	s_setprio 1
	s_waitcnt lgkmcnt(0)
	v_mfma_f32_16x16x32_bf16 v[60:63], v[138:141], v[174:177], 0
	v_mfma_f32_16x16x32_bf16 v[56:59], v[150:153], v[174:177], 0
	v_mfma_f32_16x16x32_bf16 v[44:47], v[138:141], v[182:185], 0
	v_mfma_f32_16x16x32_bf16 v[40:43], v[150:153], v[182:185], 0
	v_mfma_f32_16x16x32_bf16 v[28:31], v[138:141], v[190:193], 0
	v_mfma_f32_16x16x32_bf16 v[24:27], v[150:153], v[190:193], 0
	v_mfma_f32_16x16x32_bf16 v[12:15], v[138:141], v[198:201], 0
	v_mfma_f32_16x16x32_bf16 v[8:11], v[150:153], v[198:201], 0
	v_mfma_f32_16x16x32_bf16 v[60:63], v[146:149], v[178:181], v[60:63]
	v_mfma_f32_16x16x32_bf16 v[56:59], v[154:157], v[178:181], v[56:59]
	v_mfma_f32_16x16x32_bf16 v[44:47], v[146:149], v[186:189], v[44:47]
	v_mfma_f32_16x16x32_bf16 v[40:43], v[154:157], v[186:189], v[40:43]
	v_mfma_f32_16x16x32_bf16 v[28:31], v[146:149], v[194:197], v[28:31]
	v_mfma_f32_16x16x32_bf16 v[24:27], v[154:157], v[194:197], v[24:27]
	v_mfma_f32_16x16x32_bf16 v[12:15], v[146:149], v[202:205], v[12:15]
	v_mfma_f32_16x16x32_bf16 v[8:11], v[154:157], v[202:205], v[8:11]
	s_setprio 0
	s_setprio 1
	v_mfma_f32_16x16x32_bf16 v[52:55], v[158:161], v[174:177], 0
	v_mfma_f32_16x16x32_bf16 v[48:51], v[166:169], v[174:177], 0
	v_mfma_f32_16x16x32_bf16 v[36:39], v[158:161], v[182:185], 0
	v_mfma_f32_16x16x32_bf16 v[32:35], v[166:169], v[182:185], 0
	v_mfma_f32_16x16x32_bf16 v[20:23], v[158:161], v[190:193], 0
	v_mfma_f32_16x16x32_bf16 v[16:19], v[166:169], v[190:193], 0
	v_mfma_f32_16x16x32_bf16 v[4:7], v[158:161], v[198:201], 0
	v_mfma_f32_16x16x32_bf16 v[0:3], v[166:169], v[198:201], 0
	v_mfma_f32_16x16x32_bf16 v[52:55], v[162:165], v[178:181], v[52:55]
	v_mfma_f32_16x16x32_bf16 v[48:51], v[170:173], v[178:181], v[48:51]
	v_mfma_f32_16x16x32_bf16 v[36:39], v[162:165], v[186:189], v[36:39]
	v_mfma_f32_16x16x32_bf16 v[32:35], v[170:173], v[186:189], v[32:35]
	v_mfma_f32_16x16x32_bf16 v[20:23], v[162:165], v[194:197], v[20:23]
	v_mfma_f32_16x16x32_bf16 v[16:19], v[170:173], v[194:197], v[16:19]
	v_mfma_f32_16x16x32_bf16 v[4:7], v[162:165], v[202:205], v[4:7]
	v_mfma_f32_16x16x32_bf16 v[0:3], v[170:173], v[202:205], v[0:3]
	s_setprio 0
	s_barrier
	s_branch .Lzmid_4

.LBB0_1491:
	s_ashr_i32 s23, s22, 31
	s_lshl_b64 s[24:25], s[22:23], 21
	s_add_u32 s24, s70, s24
	s_addc_u32 s25, s71, s25
	s_and_b64 s[26:27], s[4:5], exec
	s_cselect_b32 s23, s25, s35
	s_cselect_b32 s56, s24, s34
	s_ashr_i32 s21, s20, 31
	s_lshl_b64 s[26:27], s[20:21], 21
	s_add_u32 s26, s72, s26
	s_addc_u32 s27, s76, s27
	s_and_b64 s[36:37], s[4:5], exec
	s_cselect_b32 s21, s27, s31
	s_cselect_b32 s57, s26, s30
	s_add_u32 s58, s30, 0x100
	s_addc_u32 s59, s31, 0
	s_add_u32 s30, s34, 0x100080
	s_addc_u32 s31, s35, 0
	s_mov_b32 s60, -2
	s_cmp_lt_u32 s55, 2
	s_cbranch_scc1 .Lzfirst_6
	s_add_u32 s34, s30, 0xfff00080
	s_addc_u32 s35, s31, -1
	s_add_i32 s61, 0, 0x10000
	s_cmp_eq_u32 s60, 60
	s_cselect_b32 s37, s23, s35
	s_cselect_b32 s36, s56, s34
	s_cselect_b32 s35, s21, s59
	s_cselect_b32 s34, s57, s58
	s_add_i32 s64, 0, 0x14000
	v_add_u32_e32 v100, s61, v220
	v_add_u32_e32 v156, s64, v220
	ds_read_b128 v[88:91], v100
	ds_read_b128 v[92:95], v100 offset:1024
	ds_read_b128 v[96:99], v100 offset:2048
	ds_read_b128 v[100:103], v100 offset:3072
	ds_read_b128 v[144:147], v156
	ds_read_b128 v[148:151], v156 offset:1024
	ds_read_b128 v[152:155], v156 offset:2048
	ds_read_b128 v[156:159], v156 offset:3072
	v_lshl_add_u64 v[202:203], s[30:31], 0, v[188:189]
	s_add_i32 m0, s78, 0xc000
	ds_read_b128 v[160:163], v221
	ds_read_b128 v[164:167], v221 offset:1024
	ds_read_b128 v[168:171], v221 offset:2048
	ds_read_b128 v[172:175], v221 offset:3072
	ds_read_b128 v[176:179], v221 offset:4096
	ds_read_b128 v[190:193], v221 offset:5120
	ds_read_b128 v[194:197], v221 offset:6144
	ds_read_b128 v[198:201], v221 offset:7168
	global_load_lds_dwordx4 v[202:203], off
	v_lshl_add_u64 v[202:203], s[30:31], 0, v[186:187]
	s_add_i32 m0, s78, 0xe000
	s_nop 0
	global_load_lds_dwordx4 v[202:203], off
	s_waitcnt vmcnt(40)
	s_waitcnt lgkmcnt(0)
	s_barrier
	s_setprio 1
	s_waitcnt lgkmcnt(0)
	v_mfma_f32_16x16x32_bf16 v[140:143], v[88:91], v[160:163], 0
	v_mfma_f32_16x16x32_bf16 v[136:139], v[96:99], v[160:163], 0
	v_mfma_f32_16x16x32_bf16 v[124:127], v[88:91], v[168:171], 0
	v_mfma_f32_16x16x32_bf16 v[120:123], v[96:99], v[168:171], 0
	v_mfma_f32_16x16x32_bf16 v[108:111], v[88:91], v[176:179], 0
	v_mfma_f32_16x16x32_bf16 v[104:107], v[96:99], v[176:179], 0
	v_mfma_f32_16x16x32_bf16 v[76:79], v[88:91], v[194:197], 0
	v_mfma_f32_16x16x32_bf16 v[72:75], v[96:99], v[194:197], 0
	v_mfma_f32_16x16x32_bf16 v[140:143], v[92:95], v[164:167], v[140:143]
	v_mfma_f32_16x16x32_bf16 v[136:139], v[100:103], v[164:167], v[136:139]
	v_mfma_f32_16x16x32_bf16 v[124:127], v[92:95], v[172:175], v[124:127]
	v_mfma_f32_16x16x32_bf16 v[120:123], v[100:103], v[172:175], v[120:123]
	v_mfma_f32_16x16x32_bf16 v[108:111], v[92:95], v[190:193], v[108:111]
	v_mfma_f32_16x16x32_bf16 v[104:107], v[100:103], v[190:193], v[104:107]
	v_mfma_f32_16x16x32_bf16 v[76:79], v[92:95], v[198:201], v[76:79]
	v_mfma_f32_16x16x32_bf16 v[72:75], v[100:103], v[198:201], v[72:75]
	s_setprio 0
	s_setprio 1
	v_mfma_f32_16x16x32_bf16 v[132:135], v[144:147], v[160:163], 0
	v_mfma_f32_16x16x32_bf16 v[128:131], v[152:155], v[160:163], 0
	v_mfma_f32_16x16x32_bf16 v[116:119], v[144:147], v[168:171], 0
	v_mfma_f32_16x16x32_bf16 v[112:115], v[152:155], v[168:171], 0
	v_mfma_f32_16x16x32_bf16 v[84:87], v[144:147], v[176:179], 0
	v_mfma_f32_16x16x32_bf16 v[80:83], v[152:155], v[176:179], 0
	v_mfma_f32_16x16x32_bf16 v[68:71], v[144:147], v[194:197], 0
	v_mfma_f32_16x16x32_bf16 v[64:67], v[152:155], v[194:197], 0
	v_mfma_f32_16x16x32_bf16 v[132:135], v[148:151], v[164:167], v[132:135]
	v_mfma_f32_16x16x32_bf16 v[128:131], v[156:159], v[164:167], v[128:131]
	v_mfma_f32_16x16x32_bf16 v[116:119], v[148:151], v[172:175], v[116:119]
	v_mfma_f32_16x16x32_bf16 v[112:115], v[156:159], v[172:175], v[112:115]
	v_mfma_f32_16x16x32_bf16 v[84:87], v[148:151], v[190:193], v[84:87]
	v_mfma_f32_16x16x32_bf16 v[80:83], v[156:159], v[190:193], v[80:83]
	v_mfma_f32_16x16x32_bf16 v[68:71], v[148:151], v[198:201], v[68:71]
	v_mfma_f32_16x16x32_bf16 v[64:67], v[156:159], v[198:201], v[64:67]
	s_setprio 0
	s_barrier
	s_add_i32 s61, s61, s77
	v_lshl_add_u64 v[202:203], s[34:35], 0, v[232:233]
	s_mov_b32 m0, s61
	ds_read_b128 v[160:163], v221 offset:16384
	ds_read_b128 v[164:167], v221 offset:17408
	ds_read_b128 v[168:171], v221 offset:18432
	ds_read_b128 v[172:175], v221 offset:19456
	ds_read_b128 v[176:179], v221 offset:20480
	ds_read_b128 v[190:193], v221 offset:21504
	ds_read_b128 v[194:197], v221 offset:22528
	ds_read_b128 v[198:201], v221 offset:23552
	global_load_lds_dwordx4 v[202:203], off
	s_add_i32 m0, s61, 0x2000
	s_add_u32 s62, s34, 0x100000
	v_lshl_add_u64 v[204:205], s[34:35], 0, v[184:185]
	s_addc_u32 s63, s35, 0
	s_add_i32 s61, s64, s77
	global_load_lds_dwordx4 v[204:205], off
	v_lshl_add_u64 v[206:207], s[62:63], 0, v[232:233]
	s_mov_b32 m0, s61
	v_lshl_add_u64 v[208:209], s[36:37], 0, v[182:183]
	global_load_lds_dwordx4 v[206:207], off
	v_lshl_add_u64 v[206:207], s[62:63], 0, v[184:185]
	s_add_i32 m0, s61, 0x2000
	s_nop 0
	global_load_lds_dwordx4 v[206:207], off
	v_lshl_add_u64 v[206:207], s[36:37], 0, v[180:181]
	s_waitcnt vmcnt(38)
	s_waitcnt lgkmcnt(0)
	s_barrier
	s_setprio 1
	s_waitcnt lgkmcnt(0)
	v_mfma_f32_16x16x32_bf16 v[60:63], v[88:91], v[160:163], 0
	v_mfma_f32_16x16x32_bf16 v[56:59], v[96:99], v[160:163], 0
	v_mfma_f32_16x16x32_bf16 v[44:47], v[88:91], v[168:171], 0
	v_mfma_f32_16x16x32_bf16 v[40:43], v[96:99], v[168:171], 0
	v_mfma_f32_16x16x32_bf16 v[28:31], v[88:91], v[176:179], 0
	v_mfma_f32_16x16x32_bf16 v[24:27], v[96:99], v[176:179], 0
	v_mfma_f32_16x16x32_bf16 v[12:15], v[88:91], v[194:197], 0
	v_mfma_f32_16x16x32_bf16 v[8:11], v[96:99], v[194:197], 0
	v_mfma_f32_16x16x32_bf16 v[60:63], v[92:95], v[164:167], v[60:63]
	v_mfma_f32_16x16x32_bf16 v[56:59], v[100:103], v[164:167], v[56:59]
	v_mfma_f32_16x16x32_bf16 v[44:47], v[92:95], v[172:175], v[44:47]
	v_mfma_f32_16x16x32_bf16 v[40:43], v[100:103], v[172:175], v[40:43]
	v_mfma_f32_16x16x32_bf16 v[28:31], v[92:95], v[190:193], v[28:31]
	v_mfma_f32_16x16x32_bf16 v[24:27], v[100:103], v[190:193], v[24:27]
	v_mfma_f32_16x16x32_bf16 v[12:15], v[92:95], v[198:201], v[12:15]
	v_mfma_f32_16x16x32_bf16 v[8:11], v[100:103], v[198:201], v[8:11]
	s_setprio 0
	s_setprio 1
	v_mfma_f32_16x16x32_bf16 v[52:55], v[144:147], v[160:163], 0
	v_mfma_f32_16x16x32_bf16 v[48:51], v[152:155], v[160:163], 0
	v_mfma_f32_16x16x32_bf16 v[36:39], v[144:147], v[168:171], 0
	v_mfma_f32_16x16x32_bf16 v[32:35], v[152:155], v[168:171], 0
	v_mfma_f32_16x16x32_bf16 v[20:23], v[144:147], v[176:179], 0
	v_mfma_f32_16x16x32_bf16 v[16:19], v[152:155], v[176:179], 0
	v_mfma_f32_16x16x32_bf16 v[4:7], v[144:147], v[194:197], 0
	v_mfma_f32_16x16x32_bf16 v[0:3], v[152:155], v[194:197], 0
	v_mfma_f32_16x16x32_bf16 v[52:55], v[148:151], v[164:167], v[52:55]
	v_mfma_f32_16x16x32_bf16 v[48:51], v[156:159], v[164:167], v[48:51]
	v_mfma_f32_16x16x32_bf16 v[36:39], v[148:151], v[172:175], v[36:39]
	v_mfma_f32_16x16x32_bf16 v[32:35], v[156:159], v[172:175], v[32:35]
	v_mfma_f32_16x16x32_bf16 v[20:23], v[148:151], v[190:193], v[20:23]
	v_mfma_f32_16x16x32_bf16 v[16:19], v[156:159], v[190:193], v[16:19]
	v_mfma_f32_16x16x32_bf16 v[4:7], v[148:151], v[198:201], v[4:7]
	v_mfma_f32_16x16x32_bf16 v[0:3], v[156:159], v[198:201], v[0:3]
	s_setprio 0
	s_barrier
	s_branch .Lzmid_6
.Lzfirst_6:
	s_add_u32 s34, s30, 0xfff00080
	s_addc_u32 s35, s31, -1
	s_add_i32 s61, 0, 0x10000
	s_cmp_eq_u32 s60, 60
	s_cselect_b32 s37, s23, s35
	s_cselect_b32 s36, s56, s34
	s_cselect_b32 s35, s21, s59
	s_cselect_b32 s34, s57, s58
	s_add_i32 s64, 0, 0x14000
	v_add_u32_e32 v100, s61, v220
	v_add_u32_e32 v156, s64, v220
	ds_read_b128 v[88:91], v100
	ds_read_b128 v[92:95], v100 offset:1024
	ds_read_b128 v[96:99], v100 offset:2048
	ds_read_b128 v[100:103], v100 offset:3072
	ds_read_b128 v[144:147], v156
	ds_read_b128 v[148:151], v156 offset:1024
	ds_read_b128 v[152:155], v156 offset:2048
	ds_read_b128 v[156:159], v156 offset:3072
	v_lshl_add_u64 v[202:203], s[30:31], 0, v[188:189]
	s_add_i32 m0, s78, 0xc000
	ds_read_b128 v[160:163], v221
	ds_read_b128 v[164:167], v221 offset:1024
	ds_read_b128 v[168:171], v221 offset:2048
	ds_read_b128 v[172:175], v221 offset:3072
	ds_read_b128 v[176:179], v221 offset:4096
	ds_read_b128 v[190:193], v221 offset:5120
	ds_read_b128 v[194:197], v221 offset:6144
	ds_read_b128 v[198:201], v221 offset:7168
	global_load_lds_dwordx4 v[202:203], off
	v_lshl_add_u64 v[202:203], s[30:31], 0, v[186:187]
	s_add_i32 m0, s78, 0xe000
	s_nop 0
	global_load_lds_dwordx4 v[202:203], off
	s_waitcnt vmcnt(8)
	s_waitcnt lgkmcnt(0)
	s_barrier
	s_setprio 1
	s_waitcnt lgkmcnt(0)
	v_mfma_f32_16x16x32_bf16 v[140:143], v[88:91], v[160:163], 0
	v_mfma_f32_16x16x32_bf16 v[136:139], v[96:99], v[160:163], 0
	v_mfma_f32_16x16x32_bf16 v[124:127], v[88:91], v[168:171], 0
	v_mfma_f32_16x16x32_bf16 v[120:123], v[96:99], v[168:171], 0
	v_mfma_f32_16x16x32_bf16 v[108:111], v[88:91], v[176:179], 0
	v_mfma_f32_16x16x32_bf16 v[104:107], v[96:99], v[176:179], 0
	v_mfma_f32_16x16x32_bf16 v[76:79], v[88:91], v[194:197], 0
	v_mfma_f32_16x16x32_bf16 v[72:75], v[96:99], v[194:197], 0
	v_mfma_f32_16x16x32_bf16 v[140:143], v[92:95], v[164:167], v[140:143]
	v_mfma_f32_16x16x32_bf16 v[136:139], v[100:103], v[164:167], v[136:139]
	v_mfma_f32_16x16x32_bf16 v[124:127], v[92:95], v[172:175], v[124:127]
	v_mfma_f32_16x16x32_bf16 v[120:123], v[100:103], v[172:175], v[120:123]
	v_mfma_f32_16x16x32_bf16 v[108:111], v[92:95], v[190:193], v[108:111]
	v_mfma_f32_16x16x32_bf16 v[104:107], v[100:103], v[190:193], v[104:107]
	v_mfma_f32_16x16x32_bf16 v[76:79], v[92:95], v[198:201], v[76:79]
	v_mfma_f32_16x16x32_bf16 v[72:75], v[100:103], v[198:201], v[72:75]
	s_setprio 0
	s_setprio 1
	v_mfma_f32_16x16x32_bf16 v[132:135], v[144:147], v[160:163], 0
	v_mfma_f32_16x16x32_bf16 v[128:131], v[152:155], v[160:163], 0
	v_mfma_f32_16x16x32_bf16 v[116:119], v[144:147], v[168:171], 0
	v_mfma_f32_16x16x32_bf16 v[112:115], v[152:155], v[168:171], 0
	v_mfma_f32_16x16x32_bf16 v[84:87], v[144:147], v[176:179], 0
	v_mfma_f32_16x16x32_bf16 v[80:83], v[152:155], v[176:179], 0
	v_mfma_f32_16x16x32_bf16 v[68:71], v[144:147], v[194:197], 0
	v_mfma_f32_16x16x32_bf16 v[64:67], v[152:155], v[194:197], 0
	v_mfma_f32_16x16x32_bf16 v[132:135], v[148:151], v[164:167], v[132:135]
	v_mfma_f32_16x16x32_bf16 v[128:131], v[156:159], v[164:167], v[128:131]
	v_mfma_f32_16x16x32_bf16 v[116:119], v[148:151], v[172:175], v[116:119]
	v_mfma_f32_16x16x32_bf16 v[112:115], v[156:159], v[172:175], v[112:115]
	v_mfma_f32_16x16x32_bf16 v[84:87], v[148:151], v[190:193], v[84:87]
	v_mfma_f32_16x16x32_bf16 v[80:83], v[156:159], v[190:193], v[80:83]
	v_mfma_f32_16x16x32_bf16 v[68:71], v[148:151], v[198:201], v[68:71]
	v_mfma_f32_16x16x32_bf16 v[64:67], v[156:159], v[198:201], v[64:67]
	s_setprio 0
	s_barrier
	s_add_i32 s61, s61, s77
	v_lshl_add_u64 v[202:203], s[34:35], 0, v[232:233]
	s_mov_b32 m0, s61
	ds_read_b128 v[160:163], v221 offset:16384
	ds_read_b128 v[164:167], v221 offset:17408
	ds_read_b128 v[168:171], v221 offset:18432
	ds_read_b128 v[172:175], v221 offset:19456
	ds_read_b128 v[176:179], v221 offset:20480
	ds_read_b128 v[190:193], v221 offset:21504
	ds_read_b128 v[194:197], v221 offset:22528
	ds_read_b128 v[198:201], v221 offset:23552
	global_load_lds_dwordx4 v[202:203], off
	s_add_i32 m0, s61, 0x2000
	s_add_u32 s62, s34, 0x100000
	v_lshl_add_u64 v[204:205], s[34:35], 0, v[184:185]
	s_addc_u32 s63, s35, 0
	s_add_i32 s61, s64, s77
	global_load_lds_dwordx4 v[204:205], off
	v_lshl_add_u64 v[206:207], s[62:63], 0, v[232:233]
	s_mov_b32 m0, s61
	v_lshl_add_u64 v[208:209], s[36:37], 0, v[182:183]
	global_load_lds_dwordx4 v[206:207], off
	v_lshl_add_u64 v[206:207], s[62:63], 0, v[184:185]
	s_add_i32 m0, s61, 0x2000
	s_nop 0
	global_load_lds_dwordx4 v[206:207], off
	v_lshl_add_u64 v[206:207], s[36:37], 0, v[180:181]
	s_waitcnt vmcnt(6)
	s_waitcnt lgkmcnt(0)
	s_barrier
	s_setprio 1
	s_waitcnt lgkmcnt(0)
	v_mfma_f32_16x16x32_bf16 v[60:63], v[88:91], v[160:163], 0
	v_mfma_f32_16x16x32_bf16 v[56:59], v[96:99], v[160:163], 0
	v_mfma_f32_16x16x32_bf16 v[44:47], v[88:91], v[168:171], 0
	v_mfma_f32_16x16x32_bf16 v[40:43], v[96:99], v[168:171], 0
	v_mfma_f32_16x16x32_bf16 v[28:31], v[88:91], v[176:179], 0
	v_mfma_f32_16x16x32_bf16 v[24:27], v[96:99], v[176:179], 0
	v_mfma_f32_16x16x32_bf16 v[12:15], v[88:91], v[194:197], 0
	v_mfma_f32_16x16x32_bf16 v[8:11], v[96:99], v[194:197], 0
	v_mfma_f32_16x16x32_bf16 v[60:63], v[92:95], v[164:167], v[60:63]
	v_mfma_f32_16x16x32_bf16 v[56:59], v[100:103], v[164:167], v[56:59]
	v_mfma_f32_16x16x32_bf16 v[44:47], v[92:95], v[172:175], v[44:47]
	v_mfma_f32_16x16x32_bf16 v[40:43], v[100:103], v[172:175], v[40:43]
	v_mfma_f32_16x16x32_bf16 v[28:31], v[92:95], v[190:193], v[28:31]
	v_mfma_f32_16x16x32_bf16 v[24:27], v[100:103], v[190:193], v[24:27]
	v_mfma_f32_16x16x32_bf16 v[12:15], v[92:95], v[198:201], v[12:15]
	v_mfma_f32_16x16x32_bf16 v[8:11], v[100:103], v[198:201], v[8:11]
	s_setprio 0
	s_setprio 1
	v_mfma_f32_16x16x32_bf16 v[52:55], v[144:147], v[160:163], 0
	v_mfma_f32_16x16x32_bf16 v[48:51], v[152:155], v[160:163], 0
	v_mfma_f32_16x16x32_bf16 v[36:39], v[144:147], v[168:171], 0
	v_mfma_f32_16x16x32_bf16 v[32:35], v[152:155], v[168:171], 0
	v_mfma_f32_16x16x32_bf16 v[20:23], v[144:147], v[176:179], 0
	v_mfma_f32_16x16x32_bf16 v[16:19], v[152:155], v[176:179], 0
	v_mfma_f32_16x16x32_bf16 v[4:7], v[144:147], v[194:197], 0
	v_mfma_f32_16x16x32_bf16 v[0:3], v[152:155], v[194:197], 0
	v_mfma_f32_16x16x32_bf16 v[52:55], v[148:151], v[164:167], v[52:55]
	v_mfma_f32_16x16x32_bf16 v[48:51], v[156:159], v[164:167], v[48:51]
	v_mfma_f32_16x16x32_bf16 v[36:39], v[148:151], v[172:175], v[36:39]
	v_mfma_f32_16x16x32_bf16 v[32:35], v[156:159], v[172:175], v[32:35]
	v_mfma_f32_16x16x32_bf16 v[20:23], v[148:151], v[190:193], v[20:23]
	v_mfma_f32_16x16x32_bf16 v[16:19], v[156:159], v[190:193], v[16:19]
	v_mfma_f32_16x16x32_bf16 v[4:7], v[148:151], v[198:201], v[4:7]
	v_mfma_f32_16x16x32_bf16 v[0:3], v[156:159], v[198:201], v[0:3]
	s_setprio 0
	s_barrier
	s_branch .Lzmid_6
